# dilated attention tiles kt=3,2,1: wave-uniform fast path (all keys inside window and sequence) replaces per-element mask/bias code by fma + fmamk; slow path kept for boundary tiles
# speedup vs baseline: 1.0122x; 1.0057x over previous
; __device__ __forceinline__ void dil_unit(const bf16_t* QKV, float* scr, bf16_t* O, int b, int h, int blk, char* shm) {
;     ...
;             const int k = wid + 8 * rep, res = k & (d - 1), c = k >> lg, tq0 = T0 + res + d * 32 * c;
;             const int tq = tq0 + d * r32;
;             bf16x8 qf[4];
; #pragma unroll
;             for (int s = 0; s < 4; ++s) qf[s] = *(const bf16x8*)(Qh + (rb + tq) * 1536 + s * 16 + hi * 8);
;             f32x16 o[2]; o[0] = f32x16{}; o[1] = f32x16{};
;             float mrun = -1e30f, lrun = 0.f;
;     ...
;             DIL_LOAD(4, kfA, vrA);
;             DIL_LOAD(3, kfB, vrB);
;             DIL_LOAD(2, kfC, vrC);
.LBB0_1247:
	s_add_i32 s0, s0, s28
	s_bfm_b32 s1, s30, 0
	s_and_b32 s1, s0, s1
	s_ashr_i32 s0, s0, s30
	s_add_i32 s8, s1, s93
	s_lshl_b32 s0, s0, s34
	s_add_i32 s8, s8, s0
	v_add_u32_e32 v174, s8, v180
	v_ashrrev_i32_e32 v175, 31, v174
	v_lshl_add_u64 v[172:173], v[174:175], 0, s[18:19]
	v_mad_u64_u32 v[0:1], s[0:1], v172, s81, v[160:161]
	v_mad_i32_i24 v1, v173, s81, v1
	s_mov_b32 s0, 4
	global_load_dwordx4 v[48:51], v[0:1], off
	global_load_dwordx4 v[52:55], v[0:1], off offset:32
	global_load_dwordx4 v[56:59], v[0:1], off offset:64
	global_load_dwordx4 v[60:63], v[0:1], off offset:96
	s_lshl_b32 s0, s0, 5
	s_add_i32 s3, s0, 0xffffff80
	v_or_b32_e32 v0, s3, v167
	v_lshlrev_b32_e32 v0, s30, v0
	v_add_u32_e32 v0, s8, v0
	v_max_i32_e32 v0, 0, v0
	v_add_u32_e32 v0, s18, v0
	v_mad_u64_u32 v[4:5], s[0:1], v0, s81, v[162:163]
	v_or_b32_e32 v28, s3, v176
	global_load_dwordx4 v[0:3], v[4:5], off
	global_load_dwordx4 v[24:27], v[4:5], off offset:32
	global_load_dwordx4 v[20:23], v[4:5], off offset:64
	global_load_dwordx4 v[16:19], v[4:5], off offset:96
	v_lshlrev_b32_e32 v4, s30, v28
	v_or_b32_e32 v8, 8, v28
	v_add_u32_e32 v4, s8, v4
	v_lshlrev_b32_e32 v8, s30, v8
	v_or_b32_e32 v12, 16, v28
	v_max_i32_e32 v4, 0, v4
	v_add_u32_e32 v8, s8, v8
	v_lshlrev_b32_e32 v12, s30, v12
	v_or_b32_e32 v28, 24, v28
	v_add_u32_e32 v4, s18, v4
	v_max_i32_e32 v8, 0, v8
	v_add_u32_e32 v12, s8, v12
	v_lshlrev_b32_e32 v28, s30, v28
	v_mad_u64_u32 v[4:5], s[0:1], v4, s81, v[164:165]
	v_add_u32_e32 v8, s18, v8
	v_max_i32_e32 v12, 0, v12
	v_add_u32_e32 v28, s8, v28
	global_load_dwordx4 v[4:7], v[4:5], off
	v_mad_u64_u32 v[8:9], s[0:1], v8, s81, v[164:165]
	v_add_u32_e32 v12, s18, v12
	v_max_i32_e32 v28, 0, v28
	global_load_dwordx4 v[8:11], v[8:9], off
	v_mad_u64_u32 v[12:13], s[0:1], v12, s81, v[164:165]
	v_add_u32_e32 v28, s18, v28
	global_load_dwordx4 v[12:15], v[12:13], off
	v_mad_u64_u32 v[28:29], s[0:1], v28, s81, v[164:165]
	global_load_dwordx4 v[28:31], v[28:29], off
	s_mov_b32 s0, 3
	s_lshl_b32 s0, s0, 5
	s_add_i32 s3, s0, 0xffffff80
	v_or_b32_e32 v32, s3, v167
	v_lshlrev_b32_e32 v32, s30, v32
	v_add_u32_e32 v32, s8, v32
	v_max_i32_e32 v32, 0, v32
	v_add_u32_e32 v32, s18, v32
	v_mad_u64_u32 v[36:37], s[0:1], v32, s81, v[162:163]
	s_waitcnt vmcnt(16)
	v_or_b32_e32 v64, s3, v176
	global_load_dwordx4 v[32:35], v[36:37], off
	global_load_dwordx4 v[132:135], v[36:37], off offset:32
	global_load_dwordx4 v[128:131], v[36:37], off offset:64
	global_load_dwordx4 v[124:127], v[36:37], off offset:96
	v_lshlrev_b32_e32 v36, s30, v64
	v_or_b32_e32 v40, 8, v64
	v_or_b32_e32 v44, 16, v64
	v_or_b32_e32 v64, 24, v64
	v_lshlrev_b32_e32 v40, s30, v40
	v_lshlrev_b32_e32 v44, s30, v44
	v_lshlrev_b32_e32 v64, s30, v64
	v_add_u32_e32 v36, s8, v36
	v_add_u32_e32 v40, s8, v40
	v_add_u32_e32 v44, s8, v44
	v_add_u32_e32 v64, s8, v64
	v_max_i32_e32 v36, 0, v36
	v_max_i32_e32 v40, 0, v40
	v_max_i32_e32 v44, 0, v44
	v_max_i32_e32 v64, 0, v64
	v_add_u32_e32 v36, s18, v36
	v_add_u32_e32 v40, s18, v40
	v_add_u32_e32 v44, s18, v44
	v_add_u32_e32 v64, s18, v64
	v_mad_u64_u32 v[36:37], s[0:1], v36, s81, v[164:165]
	v_mad_u64_u32 v[40:41], s[0:1], v40, s81, v[164:165]
	v_mad_u64_u32 v[44:45], s[0:1], v44, s81, v[164:165]
	v_mad_u64_u32 v[64:65], s[0:1], v64, s81, v[164:165]
	s_mov_b32 s0, 2
	global_load_dwordx4 v[36:39], v[36:37], off
	s_nop 0
	global_load_dwordx4 v[40:43], v[40:41], off
	s_nop 0
	global_load_dwordx4 v[44:47], v[44:45], off
	s_nop 0
	global_load_dwordx4 v[136:139], v[64:65], off
	s_lshl_b32 s0, s0, 5
	s_add_i32 s3, s0, 0xffffff80
	v_or_b32_e32 v64, s3, v167
	v_or_b32_e32 v78, s3, v176
	v_lshlrev_b32_e32 v64, s30, v64
	v_lshlrev_b32_e32 v76, s30, v78
	v_add_u32_e32 v64, s8, v64
	v_add_u32_e32 v76, s8, v76
	v_max_i32_e32 v64, 0, v64
	v_max_i32_e32 v76, 0, v76
	v_add_u32_e32 v64, s18, v64
	v_add_u32_e32 v76, s18, v76
	v_mad_u64_u32 v[64:65], s[0:1], v64, s81, v[162:163]
	v_mad_u64_u32 v[76:77], s[0:1], v76, s81, v[164:165]
	global_load_dwordx4 v[92:95], v[64:65], off
	global_load_dwordx4 v[72:75], v[64:65], off offset:32
	global_load_dwordx4 v[68:71], v[64:65], off offset:64
	s_nop 0
	global_load_dwordx4 v[64:67], v[64:65], off offset:96
	s_not_b32 s3, s8
	global_load_dwordx4 v[112:115], v[76:77], off
	v_or_b32_e32 v76, 8, v78
	v_lshlrev_b32_e32 v76, s30, v76
	v_add_u32_e32 v76, s8, v76
	v_max_i32_e32 v76, 0, v76
	v_add_u32_e32 v76, s18, v76
	v_mad_u64_u32 v[76:77], s[0:1], v76, s81, v[164:165]
	global_load_dwordx4 v[116:119], v[76:77], off
	v_or_b32_e32 v76, 16, v78
	v_lshlrev_b32_e32 v76, s30, v76
	v_add_u32_e32 v76, s8, v76
	v_max_i32_e32 v76, 0, v76
	v_add_u32_e32 v76, s18, v76
	v_mad_u64_u32 v[76:77], s[0:1], v76, s81, v[164:165]
	global_load_dwordx4 v[120:123], v[76:77], off
	v_or_b32_e32 v76, 24, v78
	v_lshlrev_b32_e32 v76, s30, v76
	v_add_u32_e32 v76, s8, v76
	v_max_i32_e32 v76, 0, v76
	v_add_u32_e32 v76, s18, v76
	v_mad_u64_u32 v[76:77], s[0:1], v76, s81, v[164:165]
	s_mov_b32 s0, 4
	global_load_dwordx4 v[140:143], v[76:77], off
	s_waitcnt lgkmcnt(0)
	s_waitcnt vmcnt(19)
	ds_write_b128 v178, v[4:7]
	s_waitcnt vmcnt(18)
	ds_write_b128 v178, v[8:11] offset:512
	s_waitcnt vmcnt(17)
	ds_write_b128 v178, v[12:15] offset:1024
	s_waitcnt vmcnt(16)
	ds_write_b128 v178, v[28:31] offset:1536
	v_mfma_f32_32x32x16_bf16 v[0:15], v[0:3], v[48:51], 0
	v_mfma_f32_32x32x16_bf16 v[0:15], v[24:27], v[52:55], v[0:15]
	v_mfma_f32_32x32x16_bf16 v[0:15], v[20:23], v[56:59], v[0:15]
	v_mfma_f32_32x32x16_bf16 v[0:15], v[16:19], v[60:63], v[0:15]
	v_lshl_add_u32 v16, s0, 5, v177
	v_sub_u32_e32 v17, v167, v16
	v_cvt_f32_i32_e32 v211, v17
	v_lshlrev_b32_e32 v18, s30, v16
	v_cmp_gt_u32_e32 vcc, s6, v17
	v_cmp_lt_i32_e64 s[0:1], s3, v18
	v_or_b32_e32 v17, 1, v16
	s_nop 4
	v_mov_b32_e32 v170, v0
	v_pk_mul_f32 v[18:19], v[170:171], v[210:211]
	s_and_b64 vcc, vcc, s[0:1]
	v_sub_f32_e32 v0, v18, v19
	v_sub_u32_e32 v18, v167, v17
	v_cvt_f32_i32_e32 v211, v18
	v_lshlrev_b32_e32 v17, s30, v17
	v_mov_b32_e32 v170, v1
	v_cndmask_b32_e32 v0, v243, v0, vcc
	v_cmp_gt_u32_e32 vcc, s6, v18
	v_cmp_lt_i32_e64 s[0:1], s3, v17
	v_pk_mul_f32 v[18:19], v[170:171], v[210:211]
	v_or_b32_e32 v17, 2, v16
	v_sub_f32_e32 v1, v18, v19
	v_sub_u32_e32 v18, v167, v17
	v_cvt_f32_i32_e32 v211, v18
	s_and_b64 vcc, vcc, s[0:1]
	v_lshlrev_b32_e32 v17, s30, v17
	v_mov_b32_e32 v170, v2
	v_cndmask_b32_e32 v1, v243, v1, vcc
	v_cmp_gt_u32_e32 vcc, s6, v18
	v_cmp_lt_i32_e64 s[0:1], s3, v17
	v_pk_mul_f32 v[18:19], v[170:171], v[210:211]
	s_and_b64 vcc, vcc, s[0:1]
	v_sub_f32_e32 v2, v18, v19
	v_cndmask_b32_e32 v17, v243, v2, vcc
	v_or_b32_e32 v2, 3, v16
	v_sub_u32_e32 v18, v167, v2
	v_cvt_f32_i32_e32 v211, v18
	v_lshlrev_b32_e32 v2, s30, v2
	v_mov_b32_e32 v170, v3
	v_cmp_gt_u32_e32 vcc, s6, v18
	v_cmp_lt_i32_e64 s[0:1], s3, v2
	v_pk_mul_f32 v[2:3], v[170:171], v[210:211]
	s_and_b64 vcc, vcc, s[0:1]
	v_sub_f32_e32 v2, v2, v3
	v_cndmask_b32_e32 v19, v243, v2, vcc
	v_or_b32_e32 v2, 8, v16
	v_sub_u32_e32 v3, v167, v2
	v_cvt_f32_i32_e32 v211, v3
	v_lshlrev_b32_e32 v2, s30, v2
	v_mov_b32_e32 v170, v4
	v_cmp_gt_u32_e32 vcc, s6, v3
	v_cmp_lt_i32_e64 s[0:1], s3, v2
	v_pk_mul_f32 v[2:3], v[170:171], v[210:211]
	s_and_b64 vcc, vcc, s[0:1]
	v_sub_f32_e32 v2, v2, v3
	v_cndmask_b32_e32 v4, v243, v2, vcc
	v_or_b32_e32 v2, 9, v16
	v_sub_u32_e32 v3, v167, v2
	v_cvt_f32_i32_e32 v211, v3
	v_lshlrev_b32_e32 v2, s30, v2
	v_mov_b32_e32 v170, v5
	v_cmp_gt_u32_e32 vcc, s6, v3
	v_cmp_lt_i32_e64 s[0:1], s3, v2
	v_pk_mul_f32 v[2:3], v[170:171], v[210:211]
	s_and_b64 vcc, vcc, s[0:1]
	v_sub_f32_e32 v2, v2, v3
	v_cndmask_b32_e32 v5, v243, v2, vcc
	v_or_b32_e32 v2, 10, v16
	v_sub_u32_e32 v3, v167, v2
	v_cvt_f32_i32_e32 v211, v3
	v_lshlrev_b32_e32 v2, s30, v2
	v_mov_b32_e32 v170, v6
	v_cmp_gt_u32_e32 vcc, s6, v3
	v_cmp_lt_i32_e64 s[0:1], s3, v2
	v_pk_mul_f32 v[2:3], v[170:171], v[210:211]
	s_and_b64 vcc, vcc, s[0:1]
	v_sub_f32_e32 v2, v2, v3
	v_cndmask_b32_e32 v6, v243, v2, vcc
	v_or_b32_e32 v2, 11, v16
	v_sub_u32_e32 v3, v167, v2
	v_cvt_f32_i32_e32 v211, v3
	v_lshlrev_b32_e32 v2, s30, v2
	v_mov_b32_e32 v170, v7
	v_cmp_gt_u32_e32 vcc, s6, v3
	v_cmp_lt_i32_e64 s[0:1], s3, v2
	v_pk_mul_f32 v[2:3], v[170:171], v[210:211]
	s_and_b64 vcc, vcc, s[0:1]
	v_sub_f32_e32 v2, v2, v3
	v_cndmask_b32_e32 v7, v243, v2, vcc
	v_or_b32_e32 v2, 16, v16
	v_sub_u32_e32 v3, v167, v2
	v_cvt_f32_i32_e32 v211, v3
	v_lshlrev_b32_e32 v2, s30, v2
	v_mov_b32_e32 v170, v8
	v_cmp_gt_u32_e32 vcc, s6, v3
	v_cmp_lt_i32_e64 s[0:1], s3, v2
	v_pk_mul_f32 v[2:3], v[170:171], v[210:211]
	s_and_b64 vcc, vcc, s[0:1]
	v_sub_f32_e32 v2, v2, v3
	v_cndmask_b32_e32 v8, v243, v2, vcc
	v_or_b32_e32 v2, 17, v16
	v_sub_u32_e32 v3, v167, v2
	v_cvt_f32_i32_e32 v211, v3
	v_lshlrev_b32_e32 v2, s30, v2
	v_mov_b32_e32 v170, v9
	v_cmp_gt_u32_e32 vcc, s6, v3
	v_cmp_lt_i32_e64 s[0:1], s3, v2
	v_pk_mul_f32 v[2:3], v[170:171], v[210:211]
	s_and_b64 vcc, vcc, s[0:1]
	v_sub_f32_e32 v2, v2, v3
	v_cndmask_b32_e32 v9, v243, v2, vcc
	v_or_b32_e32 v2, 18, v16
	v_sub_u32_e32 v3, v167, v2
	v_cvt_f32_i32_e32 v211, v3
	v_lshlrev_b32_e32 v2, s30, v2
	v_mov_b32_e32 v170, v10
	v_cmp_gt_u32_e32 vcc, s6, v3
	v_cmp_lt_i32_e64 s[0:1], s3, v2
	v_pk_mul_f32 v[2:3], v[170:171], v[210:211]
	s_and_b64 vcc, vcc, s[0:1]
	v_sub_f32_e32 v2, v2, v3
	v_cndmask_b32_e32 v10, v243, v2, vcc
	v_or_b32_e32 v2, 19, v16
	v_sub_u32_e32 v3, v167, v2
	v_cvt_f32_i32_e32 v211, v3
	v_lshlrev_b32_e32 v2, s30, v2
	v_mov_b32_e32 v170, v11
	v_cmp_gt_u32_e32 vcc, s6, v3
	v_cmp_lt_i32_e64 s[0:1], s3, v2
	v_pk_mul_f32 v[2:3], v[170:171], v[210:211]
	s_and_b64 vcc, vcc, s[0:1]
	v_sub_f32_e32 v2, v2, v3
	v_cndmask_b32_e32 v11, v243, v2, vcc
	v_or_b32_e32 v2, 24, v16
	v_sub_u32_e32 v3, v167, v2
	v_cvt_f32_i32_e32 v211, v3
	v_lshlrev_b32_e32 v2, s30, v2
	v_mov_b32_e32 v170, v12
	v_cmp_gt_u32_e32 vcc, s6, v3
	v_cmp_lt_i32_e64 s[0:1], s3, v2
	v_pk_mul_f32 v[2:3], v[170:171], v[210:211]
	s_and_b64 vcc, vcc, s[0:1]
	v_sub_f32_e32 v2, v2, v3
	v_cndmask_b32_e32 v12, v243, v2, vcc
	v_or_b32_e32 v2, 25, v16
	v_sub_u32_e32 v3, v167, v2
	v_cvt_f32_i32_e32 v211, v3
	v_lshlrev_b32_e32 v2, s30, v2
	v_mov_b32_e32 v170, v13
	v_cmp_gt_u32_e32 vcc, s6, v3
	v_cmp_lt_i32_e64 s[0:1], s3, v2
	v_pk_mul_f32 v[2:3], v[170:171], v[210:211]
	s_and_b64 vcc, vcc, s[0:1]
	v_sub_f32_e32 v2, v2, v3
	v_cndmask_b32_e32 v13, v243, v2, vcc
	v_or_b32_e32 v2, 26, v16
	v_sub_u32_e32 v3, v167, v2
	v_cvt_f32_i32_e32 v211, v3
	v_lshlrev_b32_e32 v2, s30, v2
	v_mov_b32_e32 v170, v14
	v_cmp_gt_u32_e32 vcc, s6, v3
	v_cmp_lt_i32_e64 s[0:1], s3, v2
	v_pk_mul_f32 v[2:3], v[170:171], v[210:211]
	s_and_b64 vcc, vcc, s[0:1]
	v_sub_f32_e32 v2, v2, v3
	v_cndmask_b32_e32 v14, v243, v2, vcc
	v_or_b32_e32 v2, 27, v16
	v_sub_u32_e32 v3, v167, v2
	v_cvt_f32_i32_e32 v211, v3
	v_lshlrev_b32_e32 v2, s30, v2
	v_mov_b32_e32 v170, v15
	v_cmp_gt_u32_e32 vcc, s6, v3
	v_cmp_lt_i32_e64 s[0:1], s3, v2
	v_pk_mul_f32 v[2:3], v[170:171], v[210:211]
; __device__ __forceinline__ void dil_unit(const bf16_t* QKV, float* scr, bf16_t* O, int b, int h, int blk, char* shm) {
;     ...
;                 DIL_LOAD(1, kfA, vrA);
;                 DIL_TILE(3, kfB, vrB);
;                 if (DIL_LIVE(2)) {
;                     DIL_LOAD(0, kfB, vrB);
;                     DIL_TILE(2, kfC, vrC);
	s_and_b64 vcc, vcc, s[0:1]
	v_sub_f32_e32 v2, v2, v3
	v_cndmask_b32_e32 v2, v243, v2, vcc
	v_max_f32_e32 v20, v14, v2
	v_max_f32_e32 v3, v17, v19
	v_max_f32_e32 v15, v6, v7
	v_max_f32_e32 v16, v8, v9
	v_max_f32_e32 v18, v10, v11
	v_max3_f32 v20, v12, v13, v20
	v_max3_f32 v3, v0, v1, v3
	v_max3_f32 v15, v4, v5, v15
	v_max3_f32 v16, v16, v18, v20
	v_max3_f32 v3, v3, v15, v16
	v_mov_b32_e32 v15, v3
	s_nop 1
	v_permlane32_swap_b32_e32 v3, v15
	s_mov_b32 s0, 0xf149f2ca
	v_max3_f32 v144, v3, v15, s0
	v_sub_f32_e32 v0, v0, v144
	v_exp_f32_e32 v16, v0
	v_sub_f32_e32 v0, v1, v144
	v_exp_f32_e32 v18, v0
	v_sub_f32_e32 v0, v17, v144
	v_exp_f32_e32 v20, v0
	v_sub_f32_e32 v0, v19, v144
	v_exp_f32_e32 v22, v0
	v_sub_f32_e32 v0, v4, v144
	v_exp_f32_e32 v24, v0
	v_sub_f32_e32 v0, v5, v144
	v_exp_f32_e32 v26, v0
	v_sub_f32_e32 v0, v6, v144
	v_exp_f32_e32 v28, v0
	v_sub_f32_e32 v0, v7, v144
	v_exp_f32_e32 v30, v0
	v_sub_f32_e32 v0, v8, v144
	v_exp_f32_e32 v17, v0
	v_sub_f32_e32 v0, v9, v144
	v_exp_f32_e32 v19, v0
	v_sub_f32_e32 v0, v10, v144
	v_exp_f32_e32 v21, v0
	v_sub_f32_e32 v0, v11, v144
	v_exp_f32_e32 v23, v0
	v_sub_f32_e32 v0, v12, v144
	v_exp_f32_e32 v25, v0
	v_sub_f32_e32 v0, v13, v144
	v_exp_f32_e32 v27, v0
	v_sub_f32_e32 v0, v14, v144
	v_exp_f32_e32 v29, v0
	v_sub_f32_e32 v0, v2, v144
	v_exp_f32_e32 v31, v0
	v_sub_f32_e32 v3, 0xf149f2ca, v144
	v_exp_f32_e32 v76, v3
	v_pk_add_f32 v[0:1], v[16:17], v[18:19]
	v_pk_add_f32 v[2:3], v[20:21], v[22:23]
	v_pk_add_f32 v[4:5], v[28:29], v[30:31]
	v_pk_add_f32 v[0:1], v[0:1], v[2:3]
	v_pk_add_f32 v[2:3], v[24:25], v[26:27]
	s_cmp_lt_i32 s8, s31
	v_pk_add_f32 v[2:3], v[2:3], v[4:5]
	s_nop 0
	v_pk_add_f32 v[0:1], v[0:1], v[2:3]
	s_nop 0
	v_add_f32_e32 v145, v0, v1
	v_mul_f32_e32 v0, 0, v76
	v_fmac_f32_e32 v145, 0, v76
	v_cvt_pk_bf16_f32 v76, v16, v18
	v_cvt_pk_bf16_f32 v77, v20, v22
	v_cvt_pk_bf16_f32 v78, v24, v26
	v_cvt_pk_bf16_f32 v79, v28, v30
	v_cvt_pk_bf16_f32 v80, v17, v19
	v_cvt_pk_bf16_f32 v81, v21, v23
	v_cvt_pk_bf16_f32 v82, v25, v27
	v_cvt_pk_bf16_f32 v83, v29, v31
	s_waitcnt lgkmcnt(0)
	ds_read_b64_tr_b16 v[84:85], v179
	ds_read_b64_tr_b16 v[86:87], v179 offset:512
	v_mov_b32_e32 v1, v0
	v_mov_b32_e32 v2, v0
	v_mov_b32_e32 v3, v0
	v_mov_b32_e32 v4, v0
	v_mov_b32_e32 v5, v0
	v_mov_b32_e32 v6, v0
	v_mov_b32_e32 v7, v0
	v_mov_b32_e32 v8, v0
	v_mov_b32_e32 v9, v0
	v_mov_b32_e32 v10, v0
	v_mov_b32_e32 v11, v0
	v_mov_b32_e32 v12, v0
	v_mov_b32_e32 v13, v0
	v_mov_b32_e32 v14, v0
	v_mov_b32_e32 v15, v0
	s_waitcnt lgkmcnt(0)
	s_nop 0
	v_mfma_f32_32x32x16_bf16 v[16:31], v[84:87], v[76:79], v[0:15]
	ds_read_b64_tr_b16 v[84:85], v179 offset:1024
	ds_read_b64_tr_b16 v[86:87], v179 offset:1536
	s_waitcnt lgkmcnt(0)
	v_mfma_f32_32x32x16_bf16 v[16:31], v[84:87], v[80:83], v[16:31]
	ds_read_b64_tr_b16 v[84:85], v179 offset:2048
	ds_read_b64_tr_b16 v[86:87], v179 offset:2560
	s_waitcnt lgkmcnt(0)
	v_mfma_f32_32x32x16_bf16 v[0:15], v[84:87], v[76:79], v[0:15]
	ds_read_b64_tr_b16 v[76:77], v179 offset:3072
	ds_read_b64_tr_b16 v[78:79], v179 offset:3584
	s_waitcnt lgkmcnt(0)
	v_mfma_f32_32x32x16_bf16 v[0:15], v[76:79], v[80:83], v[0:15]
	s_cbranch_scc1 .LBB0_1255
	s_mov_b32 s0, 1
	s_lshl_b32 s0, s0, 5
	s_add_i32 s9, s0, 0xffffff80
	v_or_b32_e32 v108, s9, v176
	v_or_b32_e32 v76, s9, v167
	v_lshlrev_b32_e32 v96, s30, v108
	v_or_b32_e32 v100, 8, v108
	v_or_b32_e32 v104, 16, v108
	v_or_b32_e32 v108, 24, v108
	v_lshlrev_b32_e32 v76, s30, v76
	v_lshlrev_b32_e32 v100, s30, v100
	v_lshlrev_b32_e32 v104, s30, v104
	v_lshlrev_b32_e32 v108, s30, v108
	v_add_u32_e32 v76, s8, v76
	v_add_u32_e32 v96, s8, v96
	v_add_u32_e32 v100, s8, v100
	v_add_u32_e32 v104, s8, v104
	v_add_u32_e32 v108, s8, v108
	v_max_i32_e32 v76, 0, v76
	v_max_i32_e32 v96, 0, v96
	v_max_i32_e32 v100, 0, v100
	v_max_i32_e32 v104, 0, v104
	v_max_i32_e32 v108, 0, v108
	v_add_u32_e32 v76, s18, v76
	v_add_u32_e32 v96, s18, v96
	v_add_u32_e32 v100, s18, v100
	v_add_u32_e32 v104, s18, v104
	v_add_u32_e32 v108, s18, v108
	v_mad_u64_u32 v[88:89], s[0:1], v76, s81, v[162:163]
	v_mad_u64_u32 v[96:97], s[0:1], v96, s81, v[164:165]
	v_mad_u64_u32 v[100:101], s[0:1], v100, s81, v[164:165]
	v_mad_u64_u32 v[104:105], s[0:1], v104, s81, v[164:165]
	v_mad_u64_u32 v[108:109], s[0:1], v108, s81, v[164:165]
	s_mov_b32 s0, 3
	global_load_dwordx4 v[76:79], v[88:89], off
	global_load_dwordx4 v[80:83], v[88:89], off offset:32
	global_load_dwordx4 v[84:87], v[88:89], off offset:64
	s_nop 0
	global_load_dwordx4 v[88:91], v[88:89], off offset:96
	s_nop 0
	global_load_dwordx4 v[96:99], v[96:97], off
	s_nop 0
	global_load_dwordx4 v[100:103], v[100:101], off
	s_nop 0
	global_load_dwordx4 v[104:107], v[104:105], off
	s_nop 0
	global_load_dwordx4 v[108:111], v[108:109], off
	s_waitcnt lgkmcnt(0)
	s_waitcnt vmcnt(19)
	ds_write_b128 v178, v[36:39]
	s_waitcnt vmcnt(18)
	ds_write_b128 v178, v[40:43] offset:512
	s_waitcnt vmcnt(17)
	ds_write_b128 v178, v[44:47] offset:1024
	s_waitcnt vmcnt(16)
	ds_write_b128 v178, v[136:139] offset:1536
	v_mfma_f32_32x32x16_bf16 v[32:47], v[32:35], v[48:51], 0
	v_mfma_f32_32x32x16_bf16 v[32:47], v[132:135], v[52:55], v[32:47]
	v_mfma_f32_32x32x16_bf16 v[32:47], v[128:131], v[56:59], v[32:47]
	v_mfma_f32_32x32x16_bf16 v[32:47], v[124:127], v[60:63], v[32:47]
	v_lshl_add_u32 v124, s0, 5, v177
	v_sub_u32_e32 v170, v167, v124
	v_add_u32_e32 v211, 0xffffffe5, v170
	v_cmp_le_u32_e32 vcc, 0x66, v211
	v_lshlrev_b32_e32 v211, s30, v124
	s_nop 2
	s_cbranch_vccnz .Ldil_slow_1
	v_cmp_ge_i32_e32 vcc, s3, v211
	s_nop 3
	s_cbranch_vccnz .Ldil_slow_1
	v_cvt_f32_i32_e32 v170, v170
	v_mul_f32_e32 v170, v171, v170
	v_fma_f32 v32, v32, v210, -v170
	v_fma_f32 v33, v33, v210, -v170
	v_fmamk_f32 v33, v171, 0x3f800000, v33
	v_fma_f32 v125, v34, v210, -v170
	v_fmamk_f32 v125, v171, 0x40000000, v125
	v_fma_f32 v126, v35, v210, -v170
	v_fmamk_f32 v126, v171, 0x40400000, v126
	v_fma_f32 v127, v36, v210, -v170
	v_fmamk_f32 v127, v171, 0x41000000, v127
	v_fma_f32 v37, v37, v210, -v170
	v_fmamk_f32 v37, v171, 0x41100000, v37
	v_fma_f32 v128, v38, v210, -v170
	v_fmamk_f32 v128, v171, 0x41200000, v128
	v_fma_f32 v39, v39, v210, -v170
	v_fmamk_f32 v39, v171, 0x41300000, v39
	v_fma_f32 v129, v40, v210, -v170
	v_fmamk_f32 v129, v171, 0x41800000, v129
	v_fma_f32 v41, v41, v210, -v170
	v_fmamk_f32 v41, v171, 0x41880000, v41
	v_fma_f32 v130, v42, v210, -v170
	v_fmamk_f32 v130, v171, 0x41900000, v130
	v_fma_f32 v43, v43, v210, -v170
	v_fmamk_f32 v43, v171, 0x41980000, v43
	v_fma_f32 v131, v44, v210, -v170
	v_fmamk_f32 v131, v171, 0x41c00000, v131
	v_fma_f32 v132, v45, v210, -v170
	v_fmamk_f32 v132, v171, 0x41c80000, v132
	v_fma_f32 v133, v46, v210, -v170
	v_fmamk_f32 v133, v171, 0x41d00000, v133
	v_fma_f32 v34, v47, v210, -v170
	v_fmamk_f32 v34, v171, 0x41d80000, v34
	s_branch .Ldil_join_1
.Ldil_slow_1:
	v_sub_u32_e32 v125, v167, v124
	v_cvt_f32_i32_e32 v211, v125
	v_lshlrev_b32_e32 v126, s30, v124
	v_cmp_gt_u32_e32 vcc, s6, v125
	v_cmp_lt_i32_e64 s[0:1], s3, v126
	v_or_b32_e32 v125, 1, v124
	s_nop 4
	v_mov_b32_e32 v170, v32
	v_pk_mul_f32 v[126:127], v[170:171], v[210:211]
	s_and_b64 vcc, vcc, s[0:1]
	v_sub_f32_e32 v32, v126, v127
	v_sub_u32_e32 v126, v167, v125
	v_cvt_f32_i32_e32 v211, v126
	v_lshlrev_b32_e32 v125, s30, v125
	v_mov_b32_e32 v170, v33
	v_cndmask_b32_e32 v32, v243, v32, vcc
	v_cmp_gt_u32_e32 vcc, s6, v126
	v_cmp_lt_i32_e64 s[0:1], s3, v125
	v_pk_mul_f32 v[126:127], v[170:171], v[210:211]
	v_or_b32_e32 v125, 2, v124
	v_sub_f32_e32 v33, v126, v127
	v_sub_u32_e32 v126, v167, v125
	v_cvt_f32_i32_e32 v211, v126
	s_and_b64 vcc, vcc, s[0:1]
	v_lshlrev_b32_e32 v125, s30, v125
	v_mov_b32_e32 v170, v34
	v_cndmask_b32_e32 v33, v243, v33, vcc
	v_cmp_gt_u32_e32 vcc, s6, v126
	v_cmp_lt_i32_e64 s[0:1], s3, v125
	v_pk_mul_f32 v[126:127], v[170:171], v[210:211]
	s_and_b64 vcc, vcc, s[0:1]
	v_sub_f32_e32 v34, v126, v127
	v_cndmask_b32_e32 v125, v243, v34, vcc
	v_or_b32_e32 v34, 3, v124
	v_sub_u32_e32 v126, v167, v34
	v_cvt_f32_i32_e32 v211, v126
	v_lshlrev_b32_e32 v34, s30, v34
	v_mov_b32_e32 v170, v35
	v_cmp_gt_u32_e32 vcc, s6, v126
	v_cmp_lt_i32_e64 s[0:1], s3, v34
	v_pk_mul_f32 v[34:35], v[170:171], v[210:211]
	s_and_b64 vcc, vcc, s[0:1]
	v_sub_f32_e32 v34, v34, v35
	v_cndmask_b32_e32 v126, v243, v34, vcc
	v_or_b32_e32 v34, 8, v124
	v_sub_u32_e32 v35, v167, v34
	v_cvt_f32_i32_e32 v211, v35
	v_lshlrev_b32_e32 v34, s30, v34
	v_mov_b32_e32 v170, v36
	v_cmp_gt_u32_e32 vcc, s6, v35
	v_cmp_lt_i32_e64 s[0:1], s3, v34
	v_pk_mul_f32 v[34:35], v[170:171], v[210:211]
	s_and_b64 vcc, vcc, s[0:1]
	v_sub_f32_e32 v34, v34, v35
	v_cndmask_b32_e32 v127, v243, v34, vcc
	v_or_b32_e32 v34, 9, v124
	v_sub_u32_e32 v35, v167, v34
	v_cvt_f32_i32_e32 v211, v35
	v_lshlrev_b32_e32 v34, s30, v34
	v_mov_b32_e32 v170, v37
	v_cmp_gt_u32_e32 vcc, s6, v35
	v_cmp_lt_i32_e64 s[0:1], s3, v34
	v_pk_mul_f32 v[34:35], v[170:171], v[210:211]
	s_and_b64 vcc, vcc, s[0:1]
	v_sub_f32_e32 v34, v34, v35
	v_cndmask_b32_e32 v37, v243, v34, vcc
	v_or_b32_e32 v34, 10, v124
	v_sub_u32_e32 v35, v167, v34
	v_cvt_f32_i32_e32 v211, v35
	v_lshlrev_b32_e32 v34, s30, v34
	v_mov_b32_e32 v170, v38
	v_cmp_gt_u32_e32 vcc, s6, v35
	v_cmp_lt_i32_e64 s[0:1], s3, v34
	v_pk_mul_f32 v[34:35], v[170:171], v[210:211]
	s_and_b64 vcc, vcc, s[0:1]
	v_sub_f32_e32 v34, v34, v35
	v_cndmask_b32_e32 v128, v243, v34, vcc
	v_or_b32_e32 v34, 11, v124
	v_sub_u32_e32 v35, v167, v34
	v_cvt_f32_i32_e32 v211, v35
	v_lshlrev_b32_e32 v34, s30, v34
	v_mov_b32_e32 v170, v39
	v_cmp_gt_u32_e32 vcc, s6, v35
	v_cmp_lt_i32_e64 s[0:1], s3, v34
	v_pk_mul_f32 v[34:35], v[170:171], v[210:211]
	s_and_b64 vcc, vcc, s[0:1]
	v_sub_f32_e32 v34, v34, v35
	v_cndmask_b32_e32 v39, v243, v34, vcc
	v_or_b32_e32 v34, 16, v124
	v_sub_u32_e32 v35, v167, v34
	v_cvt_f32_i32_e32 v211, v35
	v_lshlrev_b32_e32 v34, s30, v34
	v_mov_b32_e32 v170, v40
	v_cmp_gt_u32_e32 vcc, s6, v35
	v_cmp_lt_i32_e64 s[0:1], s3, v34
	v_pk_mul_f32 v[34:35], v[170:171], v[210:211]
	s_and_b64 vcc, vcc, s[0:1]
	v_sub_f32_e32 v34, v34, v35
	v_cndmask_b32_e32 v129, v243, v34, vcc
	v_or_b32_e32 v34, 17, v124
	v_sub_u32_e32 v35, v167, v34
	v_cvt_f32_i32_e32 v211, v35
	v_lshlrev_b32_e32 v34, s30, v34
	v_mov_b32_e32 v170, v41
	v_cmp_gt_u32_e32 vcc, s6, v35
	v_cmp_lt_i32_e64 s[0:1], s3, v34
	v_pk_mul_f32 v[34:35], v[170:171], v[210:211]
	s_and_b64 vcc, vcc, s[0:1]
	v_sub_f32_e32 v34, v34, v35
	v_cndmask_b32_e32 v41, v243, v34, vcc
	v_or_b32_e32 v34, 18, v124
	v_sub_u32_e32 v35, v167, v34
	v_cvt_f32_i32_e32 v211, v35
	v_lshlrev_b32_e32 v34, s30, v34
	v_mov_b32_e32 v170, v42
	v_cmp_gt_u32_e32 vcc, s6, v35
	v_cmp_lt_i32_e64 s[0:1], s3, v34
	v_pk_mul_f32 v[34:35], v[170:171], v[210:211]
	s_and_b64 vcc, vcc, s[0:1]
	v_sub_f32_e32 v34, v34, v35
	v_cndmask_b32_e32 v130, v243, v34, vcc
	v_or_b32_e32 v34, 19, v124
	v_sub_u32_e32 v35, v167, v34
	v_cvt_f32_i32_e32 v211, v35
	v_lshlrev_b32_e32 v34, s30, v34
	v_mov_b32_e32 v170, v43
	v_cmp_gt_u32_e32 vcc, s6, v35
	v_cmp_lt_i32_e64 s[0:1], s3, v34
	v_pk_mul_f32 v[34:35], v[170:171], v[210:211]
	s_and_b64 vcc, vcc, s[0:1]
	v_sub_f32_e32 v34, v34, v35
	v_cndmask_b32_e32 v43, v243, v34, vcc
	v_or_b32_e32 v34, 24, v124
	v_sub_u32_e32 v35, v167, v34
	v_cvt_f32_i32_e32 v211, v35
	v_lshlrev_b32_e32 v34, s30, v34
	v_mov_b32_e32 v170, v44
	v_cmp_gt_u32_e32 vcc, s6, v35
	v_cmp_lt_i32_e64 s[0:1], s3, v34
	v_pk_mul_f32 v[34:35], v[170:171], v[210:211]
	s_and_b64 vcc, vcc, s[0:1]
	v_sub_f32_e32 v34, v34, v35
	v_cndmask_b32_e32 v131, v243, v34, vcc
	v_or_b32_e32 v34, 25, v124
	v_sub_u32_e32 v35, v167, v34
	v_cvt_f32_i32_e32 v211, v35
	v_lshlrev_b32_e32 v34, s30, v34
	v_mov_b32_e32 v170, v45
	v_cmp_gt_u32_e32 vcc, s6, v35
	v_cmp_lt_i32_e64 s[0:1], s3, v34
	v_pk_mul_f32 v[34:35], v[170:171], v[210:211]
	s_and_b64 vcc, vcc, s[0:1]
	v_sub_f32_e32 v34, v34, v35
	v_cndmask_b32_e32 v132, v243, v34, vcc
	v_or_b32_e32 v34, 26, v124
	v_sub_u32_e32 v35, v167, v34
	v_cvt_f32_i32_e32 v211, v35
	v_lshlrev_b32_e32 v34, s30, v34
	v_mov_b32_e32 v170, v46
	v_cmp_gt_u32_e32 vcc, s6, v35
	v_cmp_lt_i32_e64 s[0:1], s3, v34
	v_pk_mul_f32 v[34:35], v[170:171], v[210:211]
	s_and_b64 vcc, vcc, s[0:1]
	v_sub_f32_e32 v34, v34, v35
	v_cndmask_b32_e32 v133, v243, v34, vcc
	v_or_b32_e32 v34, 27, v124
	v_sub_u32_e32 v35, v167, v34
	v_cvt_f32_i32_e32 v211, v35
	v_lshlrev_b32_e32 v34, s30, v34
	v_mov_b32_e32 v170, v47
	v_cmp_gt_u32_e32 vcc, s6, v35
	v_cmp_lt_i32_e64 s[0:1], s3, v34
	v_pk_mul_f32 v[34:35], v[170:171], v[210:211]
	s_and_b64 vcc, vcc, s[0:1]
	v_sub_f32_e32 v34, v34, v35
	v_cndmask_b32_e32 v34, v243, v34, vcc
; __device__ __forceinline__ void dil_unit(const bf16_t* QKV, float* scr, bf16_t* O, int b, int h, int blk, char* shm) {
;     ...
;                 if (DIL_LIVE(2)) {
;                     DIL_LOAD(0, kfB, vrB);
;                     DIL_TILE(2, kfC, vrC);
.Ldil_join_1:
	v_max_f32_e32 v42, v133, v34
	v_max_f32_e32 v35, v125, v126
	v_max_f32_e32 v36, v128, v39
	v_max_f32_e32 v38, v129, v41
	v_max_f32_e32 v40, v130, v43
	v_max3_f32 v42, v131, v132, v42
	v_max3_f32 v35, v32, v33, v35
	v_max3_f32 v36, v127, v37, v36
	v_max3_f32 v38, v38, v40, v42
	v_max3_f32 v35, v35, v36, v38
	v_mov_b32_e32 v36, v35
	s_nop 1
	v_permlane32_swap_b32_e32 v35, v36
	v_max3_f32 v181, v144, v35, v36
	v_sub_f32_e32 v32, v32, v181
	v_exp_f32_e32 v36, v32
	v_sub_f32_e32 v32, v33, v181
	v_exp_f32_e32 v38, v32
	v_sub_f32_e32 v32, v125, v181
	v_exp_f32_e32 v40, v32
	v_sub_f32_e32 v32, v126, v181
	v_exp_f32_e32 v42, v32
	v_sub_f32_e32 v32, v127, v181
	v_exp_f32_e32 v44, v32
	v_sub_f32_e32 v32, v37, v181
	v_exp_f32_e32 v46, v32
	v_sub_f32_e32 v32, v128, v181
	v_exp_f32_e32 v124, v32
	v_sub_f32_e32 v32, v39, v181
	v_exp_f32_e32 v126, v32
	v_sub_f32_e32 v32, v129, v181
	v_exp_f32_e32 v37, v32
	v_sub_f32_e32 v32, v41, v181
	v_exp_f32_e32 v39, v32
	v_sub_f32_e32 v32, v130, v181
	v_exp_f32_e32 v41, v32
	v_sub_f32_e32 v32, v43, v181
	v_exp_f32_e32 v43, v32
	v_sub_f32_e32 v32, v131, v181
	v_exp_f32_e32 v45, v32
	v_sub_f32_e32 v32, v132, v181
	v_exp_f32_e32 v47, v32
	v_sub_f32_e32 v32, v133, v181
	v_exp_f32_e32 v125, v32
	v_sub_f32_e32 v32, v34, v181
	v_exp_f32_e32 v127, v32
	v_sub_f32_e32 v35, v144, v181
	v_exp_f32_e32 v32, v35
	v_pk_add_f32 v[34:35], v[36:37], v[38:39]
	v_pk_add_f32 v[128:129], v[40:41], v[42:43]
	v_pk_add_f32 v[130:131], v[124:125], v[126:127]
	v_pk_add_f32 v[34:35], v[34:35], v[128:129]
	v_pk_add_f32 v[128:129], v[44:45], v[46:47]
	v_pk_mul_f32 v[30:31], v[30:31], v[32:33] op_sel_hi:[1,0]
	v_pk_add_f32 v[128:129], v[128:129], v[130:131]
	v_pk_mul_f32 v[28:29], v[28:29], v[32:33] op_sel_hi:[1,0]
	v_pk_add_f32 v[34:35], v[34:35], v[128:129]
	v_pk_mul_f32 v[26:27], v[26:27], v[32:33] op_sel_hi:[1,0]
	v_add_f32_e32 v175, v34, v35
	v_pk_mul_f32 v[24:25], v[24:25], v[32:33] op_sel_hi:[1,0]
	v_pk_mul_f32 v[22:23], v[22:23], v[32:33] op_sel_hi:[1,0]
	v_pk_mul_f32 v[20:21], v[20:21], v[32:33] op_sel_hi:[1,0]
	v_pk_mul_f32 v[18:19], v[18:19], v[32:33] op_sel_hi:[1,0]
	v_pk_mul_f32 v[16:17], v[16:17], v[32:33] op_sel_hi:[1,0]
	v_pk_mul_f32 v[14:15], v[14:15], v[32:33] op_sel_hi:[1,0]
	v_pk_mul_f32 v[12:13], v[12:13], v[32:33] op_sel_hi:[1,0]
	v_pk_mul_f32 v[10:11], v[10:11], v[32:33] op_sel_hi:[1,0]
	v_pk_mul_f32 v[8:9], v[8:9], v[32:33] op_sel_hi:[1,0]
	v_pk_mul_f32 v[6:7], v[6:7], v[32:33] op_sel_hi:[1,0]
	v_pk_mul_f32 v[4:5], v[4:5], v[32:33] op_sel_hi:[1,0]
	v_pk_mul_f32 v[2:3], v[2:3], v[32:33] op_sel_hi:[1,0]
	v_pk_mul_f32 v[0:1], v[0:1], v[32:33] op_sel_hi:[1,0]
	v_fmac_f32_e32 v175, v145, v32
	v_cvt_pk_bf16_f32 v32, v36, v38
	v_cvt_pk_bf16_f32 v33, v40, v42
	v_cvt_pk_bf16_f32 v34, v44, v46
	v_cvt_pk_bf16_f32 v35, v124, v126
	v_cvt_pk_bf16_f32 v36, v37, v39
	v_cvt_pk_bf16_f32 v37, v41, v43
	v_cvt_pk_bf16_f32 v38, v45, v47
	v_cvt_pk_bf16_f32 v39, v125, v127
	s_waitcnt lgkmcnt(0)
	ds_read_b64_tr_b16 v[40:41], v179
	ds_read_b64_tr_b16 v[42:43], v179 offset:512
	s_waitcnt lgkmcnt(0)
	v_mfma_f32_32x32x16_bf16 v[16:31], v[40:43], v[32:35], v[16:31]
	ds_read_b64_tr_b16 v[40:41], v179 offset:1024
	ds_read_b64_tr_b16 v[42:43], v179 offset:1536
	s_cmp_lt_i32 s8, s35
	s_waitcnt lgkmcnt(0)
	v_mfma_f32_32x32x16_bf16 v[16:31], v[40:43], v[36:39], v[16:31]
	ds_read_b64_tr_b16 v[40:41], v179 offset:2048
	ds_read_b64_tr_b16 v[42:43], v179 offset:2560
	s_waitcnt lgkmcnt(0)
	v_mfma_f32_32x32x16_bf16 v[0:15], v[40:43], v[32:35], v[0:15]
	ds_read_b64_tr_b16 v[32:33], v179 offset:3072
	ds_read_b64_tr_b16 v[34:35], v179 offset:3584
	s_waitcnt lgkmcnt(0)
	v_mfma_f32_32x32x16_bf16 v[0:15], v[32:35], v[36:39], v[0:15]
	s_cbranch_scc1 .LBB0_1254
	s_mov_b32 s0, s19
	s_lshl_b32 s0, s0, 5
	s_add_i32 s9, s0, 0xffffff80
	v_or_b32_e32 v32, s9, v167
	v_lshlrev_b32_e32 v32, s30, v32
	v_add_u32_e32 v32, s8, v32
	v_max_i32_e32 v32, 0, v32
	v_add_u32_e32 v32, s18, v32
	v_mad_u64_u32 v[32:33], s[0:1], v32, s81, v[162:163]
	v_or_b32_e32 v34, s9, v176
	global_load_dwordx4 v[124:127], v[32:33], off
	global_load_dwordx4 v[128:131], v[32:33], off offset:32
	global_load_dwordx4 v[132:135], v[32:33], off offset:64
	global_load_dwordx4 v[136:139], v[32:33], off offset:96
	v_lshlrev_b32_e32 v32, s30, v34
	v_add_u32_e32 v32, s8, v32
	v_max_i32_e32 v32, 0, v32
	v_add_u32_e32 v32, s18, v32
	v_mad_u64_u32 v[32:33], s[0:1], v32, s81, v[164:165]
	global_load_dwordx4 v[144:147], v[32:33], off
	v_or_b32_e32 v32, 8, v34
	v_lshlrev_b32_e32 v32, s30, v32
	v_add_u32_e32 v32, s8, v32
	v_max_i32_e32 v32, 0, v32
	v_add_u32_e32 v32, s18, v32
	v_mad_u64_u32 v[32:33], s[0:1], v32, s81, v[164:165]
	global_load_dwordx4 v[148:151], v[32:33], off
	v_or_b32_e32 v32, 16, v34
	v_lshlrev_b32_e32 v32, s30, v32
	v_add_u32_e32 v32, s8, v32
	v_max_i32_e32 v32, 0, v32
	v_add_u32_e32 v32, s18, v32
	v_mad_u64_u32 v[32:33], s[0:1], v32, s81, v[164:165]
	global_load_dwordx4 v[152:155], v[32:33], off
	v_or_b32_e32 v32, 24, v34
	v_lshlrev_b32_e32 v32, s30, v32
	v_add_u32_e32 v32, s8, v32
	v_max_i32_e32 v32, 0, v32
	v_add_u32_e32 v32, s18, v32
	v_mad_u64_u32 v[32:33], s[0:1], v32, s81, v[164:165]
	global_load_dwordx4 v[156:159], v[32:33], off
	s_waitcnt vmcnt(23)
	v_mfma_f32_32x32x16_bf16 v[32:47], v[92:95], v[48:51], 0
	s_mov_b32 s0, 2
	s_waitcnt lgkmcnt(0)
	s_waitcnt vmcnt(19)
	ds_write_b128 v178, v[112:115]
	s_waitcnt vmcnt(18)
	ds_write_b128 v178, v[116:119] offset:512
	s_waitcnt vmcnt(17)
	ds_write_b128 v178, v[120:123] offset:1024
	s_waitcnt vmcnt(16)
	ds_write_b128 v178, v[140:143] offset:1536
	v_mfma_f32_32x32x16_bf16 v[32:47], v[72:75], v[52:55], v[32:47]
	v_mfma_f32_32x32x16_bf16 v[32:47], v[68:71], v[56:59], v[32:47]
	v_mfma_f32_32x32x16_bf16 v[32:47], v[64:67], v[60:63], v[32:47]
	v_lshl_add_u32 v64, s0, 5, v177
	v_sub_u32_e32 v170, v167, v64
	v_add_u32_e32 v211, 0xffffffe5, v170
	v_cmp_le_u32_e32 vcc, 0x66, v211
	v_lshlrev_b32_e32 v211, s30, v64
	s_nop 2
	s_cbranch_vccnz .Ldil_slow_2
	v_cmp_ge_i32_e32 vcc, s3, v211
	s_nop 3
	s_cbranch_vccnz .Ldil_slow_2
	v_cvt_f32_i32_e32 v170, v170
	v_mul_f32_e32 v170, v171, v170
	v_fma_f32 v32, v32, v210, -v170
	v_fma_f32 v33, v33, v210, -v170
	v_fmamk_f32 v33, v171, 0x3f800000, v33
	v_fma_f32 v65, v34, v210, -v170
	v_fmamk_f32 v65, v171, 0x40000000, v65
	v_fma_f32 v66, v35, v210, -v170
	v_fmamk_f32 v66, v171, 0x40400000, v66
	v_fma_f32 v68, v36, v210, -v170
	v_fmamk_f32 v68, v171, 0x41000000, v68
	v_fma_f32 v37, v37, v210, -v170
	v_fmamk_f32 v37, v171, 0x41100000, v37
	v_fma_f32 v69, v38, v210, -v170
	v_fmamk_f32 v69, v171, 0x41200000, v69
	v_fma_f32 v39, v39, v210, -v170
	v_fmamk_f32 v39, v171, 0x41300000, v39
	v_fma_f32 v71, v40, v210, -v170
	v_fmamk_f32 v71, v171, 0x41800000, v71
	v_fma_f32 v41, v41, v210, -v170
	v_fmamk_f32 v41, v171, 0x41880000, v41
	v_fma_f32 v72, v42, v210, -v170
	v_fmamk_f32 v72, v171, 0x41900000, v72
	v_fma_f32 v43, v43, v210, -v170
	v_fmamk_f32 v43, v171, 0x41980000, v43
	v_fma_f32 v73, v44, v210, -v170
	v_fmamk_f32 v73, v171, 0x41c00000, v73
	v_fma_f32 v74, v45, v210, -v170
	v_fmamk_f32 v74, v171, 0x41c80000, v74
	v_fma_f32 v75, v46, v210, -v170
	v_fmamk_f32 v75, v171, 0x41d00000, v75
	v_fma_f32 v34, v47, v210, -v170
	v_fmamk_f32 v34, v171, 0x41d80000, v34
	s_branch .Ldil_join_2
.Ldil_slow_2:
	v_sub_u32_e32 v65, v167, v64
	v_cvt_f32_i32_e32 v211, v65
	v_lshlrev_b32_e32 v66, s30, v64
	v_cmp_gt_u32_e32 vcc, s6, v65
	v_cmp_lt_i32_e64 s[0:1], s3, v66
	v_or_b32_e32 v65, 1, v64
	s_nop 4
	v_mov_b32_e32 v170, v32
	v_pk_mul_f32 v[66:67], v[170:171], v[210:211]
	s_and_b64 vcc, vcc, s[0:1]
	v_sub_f32_e32 v32, v66, v67
	v_sub_u32_e32 v66, v167, v65
	v_cvt_f32_i32_e32 v211, v66
	v_lshlrev_b32_e32 v65, s30, v65
	v_mov_b32_e32 v170, v33
	v_cndmask_b32_e32 v32, v243, v32, vcc
	v_cmp_gt_u32_e32 vcc, s6, v66
	v_cmp_lt_i32_e64 s[0:1], s3, v65
	v_pk_mul_f32 v[66:67], v[170:171], v[210:211]
	v_or_b32_e32 v65, 2, v64
	v_sub_f32_e32 v33, v66, v67
	v_sub_u32_e32 v66, v167, v65
	v_cvt_f32_i32_e32 v211, v66
	s_and_b64 vcc, vcc, s[0:1]
	v_lshlrev_b32_e32 v65, s30, v65
	v_mov_b32_e32 v170, v34
	v_cndmask_b32_e32 v33, v243, v33, vcc
	v_cmp_gt_u32_e32 vcc, s6, v66
	v_cmp_lt_i32_e64 s[0:1], s3, v65
	v_pk_mul_f32 v[66:67], v[170:171], v[210:211]
	s_and_b64 vcc, vcc, s[0:1]
	v_sub_f32_e32 v34, v66, v67
	v_cndmask_b32_e32 v65, v243, v34, vcc
	v_or_b32_e32 v34, 3, v64
	v_sub_u32_e32 v66, v167, v34
	v_cvt_f32_i32_e32 v211, v66
	v_lshlrev_b32_e32 v34, s30, v34
	v_mov_b32_e32 v170, v35
	v_cmp_gt_u32_e32 vcc, s6, v66
	v_cmp_lt_i32_e64 s[0:1], s3, v34
	v_pk_mul_f32 v[34:35], v[170:171], v[210:211]
	s_and_b64 vcc, vcc, s[0:1]
	v_sub_f32_e32 v34, v34, v35
	v_cndmask_b32_e32 v66, v243, v34, vcc
	v_or_b32_e32 v34, 8, v64
	v_sub_u32_e32 v35, v167, v34
	v_cvt_f32_i32_e32 v211, v35
	v_lshlrev_b32_e32 v34, s30, v34
	v_mov_b32_e32 v170, v36
	v_cmp_gt_u32_e32 vcc, s6, v35
	v_cmp_lt_i32_e64 s[0:1], s3, v34
	v_pk_mul_f32 v[34:35], v[170:171], v[210:211]
	s_and_b64 vcc, vcc, s[0:1]
	v_sub_f32_e32 v34, v34, v35
	v_cndmask_b32_e32 v68, v243, v34, vcc
	v_or_b32_e32 v34, 9, v64
	v_sub_u32_e32 v35, v167, v34
	v_cvt_f32_i32_e32 v211, v35
	v_lshlrev_b32_e32 v34, s30, v34
	v_mov_b32_e32 v170, v37
	v_cmp_gt_u32_e32 vcc, s6, v35
	v_cmp_lt_i32_e64 s[0:1], s3, v34
	v_pk_mul_f32 v[34:35], v[170:171], v[210:211]
	s_and_b64 vcc, vcc, s[0:1]
	v_sub_f32_e32 v34, v34, v35
	v_cndmask_b32_e32 v37, v243, v34, vcc
	v_or_b32_e32 v34, 10, v64
	v_sub_u32_e32 v35, v167, v34
	v_cvt_f32_i32_e32 v211, v35
	v_lshlrev_b32_e32 v34, s30, v34
	v_mov_b32_e32 v170, v38
	v_cmp_gt_u32_e32 vcc, s6, v35
	v_cmp_lt_i32_e64 s[0:1], s3, v34
	v_pk_mul_f32 v[34:35], v[170:171], v[210:211]
	s_and_b64 vcc, vcc, s[0:1]
	v_sub_f32_e32 v34, v34, v35
	v_cndmask_b32_e32 v69, v243, v34, vcc
	v_or_b32_e32 v34, 11, v64
	v_sub_u32_e32 v35, v167, v34
	v_cvt_f32_i32_e32 v211, v35
	v_lshlrev_b32_e32 v34, s30, v34
	v_mov_b32_e32 v170, v39
	v_cmp_gt_u32_e32 vcc, s6, v35
	v_cmp_lt_i32_e64 s[0:1], s3, v34
	v_pk_mul_f32 v[34:35], v[170:171], v[210:211]
	s_and_b64 vcc, vcc, s[0:1]
	v_sub_f32_e32 v34, v34, v35
	v_cndmask_b32_e32 v39, v243, v34, vcc
	v_or_b32_e32 v34, 16, v64
	v_sub_u32_e32 v35, v167, v34
	v_cvt_f32_i32_e32 v211, v35
	v_lshlrev_b32_e32 v34, s30, v34
	v_mov_b32_e32 v170, v40
	v_cmp_gt_u32_e32 vcc, s6, v35
	v_cmp_lt_i32_e64 s[0:1], s3, v34
	v_pk_mul_f32 v[34:35], v[170:171], v[210:211]
	s_and_b64 vcc, vcc, s[0:1]
	v_sub_f32_e32 v34, v34, v35
	v_cndmask_b32_e32 v71, v243, v34, vcc
	v_or_b32_e32 v34, 17, v64
	v_sub_u32_e32 v35, v167, v34
	v_cvt_f32_i32_e32 v211, v35
	v_lshlrev_b32_e32 v34, s30, v34
	v_mov_b32_e32 v170, v41
	v_cmp_gt_u32_e32 vcc, s6, v35
	v_cmp_lt_i32_e64 s[0:1], s3, v34
	v_pk_mul_f32 v[34:35], v[170:171], v[210:211]
	s_and_b64 vcc, vcc, s[0:1]
	v_sub_f32_e32 v34, v34, v35
	v_cndmask_b32_e32 v41, v243, v34, vcc
	v_or_b32_e32 v34, 18, v64
	v_sub_u32_e32 v35, v167, v34
	v_cvt_f32_i32_e32 v211, v35
	v_lshlrev_b32_e32 v34, s30, v34
	v_mov_b32_e32 v170, v42
	v_cmp_gt_u32_e32 vcc, s6, v35
	v_cmp_lt_i32_e64 s[0:1], s3, v34
	v_pk_mul_f32 v[34:35], v[170:171], v[210:211]
	s_and_b64 vcc, vcc, s[0:1]
	v_sub_f32_e32 v34, v34, v35
	v_cndmask_b32_e32 v72, v243, v34, vcc
	v_or_b32_e32 v34, 19, v64
	v_sub_u32_e32 v35, v167, v34
	v_cvt_f32_i32_e32 v211, v35
	v_lshlrev_b32_e32 v34, s30, v34
	v_mov_b32_e32 v170, v43
	v_cmp_gt_u32_e32 vcc, s6, v35
	v_cmp_lt_i32_e64 s[0:1], s3, v34
	v_pk_mul_f32 v[34:35], v[170:171], v[210:211]
	s_and_b64 vcc, vcc, s[0:1]
	v_sub_f32_e32 v34, v34, v35
	v_cndmask_b32_e32 v43, v243, v34, vcc
	v_or_b32_e32 v34, 24, v64
	v_sub_u32_e32 v35, v167, v34
	v_cvt_f32_i32_e32 v211, v35
	v_lshlrev_b32_e32 v34, s30, v34
	v_mov_b32_e32 v170, v44
	v_cmp_gt_u32_e32 vcc, s6, v35
	v_cmp_lt_i32_e64 s[0:1], s3, v34
	v_pk_mul_f32 v[34:35], v[170:171], v[210:211]
	s_and_b64 vcc, vcc, s[0:1]
	v_sub_f32_e32 v34, v34, v35
	v_cndmask_b32_e32 v73, v243, v34, vcc
	v_or_b32_e32 v34, 25, v64
	v_sub_u32_e32 v35, v167, v34
	v_cvt_f32_i32_e32 v211, v35
	v_lshlrev_b32_e32 v34, s30, v34
	v_mov_b32_e32 v170, v45
	v_cmp_gt_u32_e32 vcc, s6, v35
	v_cmp_lt_i32_e64 s[0:1], s3, v34
	v_pk_mul_f32 v[34:35], v[170:171], v[210:211]
	s_and_b64 vcc, vcc, s[0:1]
	v_sub_f32_e32 v34, v34, v35
	v_cndmask_b32_e32 v74, v243, v34, vcc
	v_or_b32_e32 v34, 26, v64
	v_sub_u32_e32 v35, v167, v34
	v_cvt_f32_i32_e32 v211, v35
	v_lshlrev_b32_e32 v34, s30, v34
	v_mov_b32_e32 v170, v46
	v_cmp_gt_u32_e32 vcc, s6, v35
	v_cmp_lt_i32_e64 s[0:1], s3, v34
	v_pk_mul_f32 v[34:35], v[170:171], v[210:211]
	s_and_b64 vcc, vcc, s[0:1]
	v_sub_f32_e32 v34, v34, v35
	v_cndmask_b32_e32 v75, v243, v34, vcc
	v_or_b32_e32 v34, 27, v64
	v_sub_u32_e32 v35, v167, v34
	v_cvt_f32_i32_e32 v211, v35
	v_lshlrev_b32_e32 v34, s30, v34
	v_mov_b32_e32 v170, v47
	v_cmp_gt_u32_e32 vcc, s6, v35
	v_cmp_lt_i32_e64 s[0:1], s3, v34
	v_pk_mul_f32 v[34:35], v[170:171], v[210:211]
	s_and_b64 vcc, vcc, s[0:1]
	v_sub_f32_e32 v34, v34, v35
	v_cndmask_b32_e32 v34, v243, v34, vcc
.Ldil_join_2:
	v_max_f32_e32 v42, v75, v34
	v_max_f32_e32 v35, v65, v66
	v_max_f32_e32 v36, v69, v39
	v_max_f32_e32 v38, v71, v41
	v_max_f32_e32 v40, v72, v43
	v_max3_f32 v42, v73, v74, v42
	v_max3_f32 v35, v32, v33, v35
	v_max3_f32 v36, v68, v37, v36
	v_max3_f32 v38, v38, v40, v42
	v_max3_f32 v35, v35, v36, v38
	v_mov_b32_e32 v36, v35
	s_nop 1
	v_permlane32_swap_b32_e32 v35, v36
	v_max3_f32 v67, v181, v35, v36
	v_sub_f32_e32 v32, v32, v67
	v_exp_f32_e32 v36, v32
	v_sub_f32_e32 v32, v33, v67
	v_exp_f32_e32 v38, v32
	v_sub_f32_e32 v32, v65, v67
	v_exp_f32_e32 v40, v32
	v_sub_f32_e32 v32, v66, v67
	v_exp_f32_e32 v42, v32
	v_sub_f32_e32 v32, v68, v67
	v_exp_f32_e32 v44, v32
	v_sub_f32_e32 v32, v37, v67
	v_exp_f32_e32 v46, v32
	v_sub_f32_e32 v32, v69, v67
	v_exp_f32_e32 v68, v32
	v_sub_f32_e32 v32, v39, v67
	v_exp_f32_e32 v70, v32
	v_sub_f32_e32 v32, v71, v67
	v_exp_f32_e32 v37, v32
	v_sub_f32_e32 v32, v41, v67
	v_exp_f32_e32 v39, v32
	v_sub_f32_e32 v32, v72, v67
	v_exp_f32_e32 v41, v32
	v_sub_f32_e32 v32, v43, v67
	v_exp_f32_e32 v43, v32
	v_sub_f32_e32 v32, v73, v67
	v_exp_f32_e32 v45, v32
	v_sub_f32_e32 v32, v74, v67
	v_exp_f32_e32 v47, v32
	v_sub_f32_e32 v32, v75, v67
	v_exp_f32_e32 v69, v32
	v_sub_f32_e32 v32, v34, v67
	v_exp_f32_e32 v71, v32
	v_sub_f32_e32 v35, v181, v67
	v_exp_f32_e32 v32, v35
	v_pk_add_f32 v[34:35], v[36:37], v[38:39]
	v_pk_add_f32 v[64:65], v[40:41], v[42:43]
	v_pk_add_f32 v[72:73], v[68:69], v[70:71]
	v_pk_add_f32 v[34:35], v[34:35], v[64:65]
	v_pk_add_f32 v[64:65], v[44:45], v[46:47]
	v_pk_mul_f32 v[30:31], v[30:31], v[32:33] op_sel_hi:[1,0]
	v_pk_add_f32 v[64:65], v[64:65], v[72:73]
	v_pk_mul_f32 v[28:29], v[28:29], v[32:33] op_sel_hi:[1,0]
	v_pk_add_f32 v[34:35], v[34:35], v[64:65]
	v_pk_mul_f32 v[26:27], v[26:27], v[32:33] op_sel_hi:[1,0]
	v_add_f32_e32 v65, v34, v35
	v_pk_mul_f32 v[24:25], v[24:25], v[32:33] op_sel_hi:[1,0]
	v_pk_mul_f32 v[22:23], v[22:23], v[32:33] op_sel_hi:[1,0]
	v_pk_mul_f32 v[20:21], v[20:21], v[32:33] op_sel_hi:[1,0]
	v_pk_mul_f32 v[18:19], v[18:19], v[32:33] op_sel_hi:[1,0]
	v_pk_mul_f32 v[16:17], v[16:17], v[32:33] op_sel_hi:[1,0]
	v_pk_mul_f32 v[14:15], v[14:15], v[32:33] op_sel_hi:[1,0]
	v_pk_mul_f32 v[12:13], v[12:13], v[32:33] op_sel_hi:[1,0]
	v_pk_mul_f32 v[10:11], v[10:11], v[32:33] op_sel_hi:[1,0]
	v_pk_mul_f32 v[8:9], v[8:9], v[32:33] op_sel_hi:[1,0]
	v_pk_mul_f32 v[6:7], v[6:7], v[32:33] op_sel_hi:[1,0]
	v_pk_mul_f32 v[4:5], v[4:5], v[32:33] op_sel_hi:[1,0]
	v_pk_mul_f32 v[2:3], v[2:3], v[32:33] op_sel_hi:[1,0]
	v_pk_mul_f32 v[0:1], v[0:1], v[32:33] op_sel_hi:[1,0]
	v_fmac_f32_e32 v65, v175, v32
	v_cvt_pk_bf16_f32 v32, v36, v38
	v_cvt_pk_bf16_f32 v33, v40, v42
	v_cvt_pk_bf16_f32 v34, v44, v46
	v_cvt_pk_bf16_f32 v35, v68, v70
	v_cvt_pk_bf16_f32 v36, v37, v39
	v_cvt_pk_bf16_f32 v37, v41, v43
	v_cvt_pk_bf16_f32 v38, v45, v47
	v_cvt_pk_bf16_f32 v39, v69, v71
	s_waitcnt lgkmcnt(0)
	ds_read_b64_tr_b16 v[40:41], v179
	ds_read_b64_tr_b16 v[42:43], v179 offset:512
	s_waitcnt lgkmcnt(0)
	v_mfma_f32_32x32x16_bf16 v[16:31], v[40:43], v[32:35], v[16:31]
	ds_read_b64_tr_b16 v[40:41], v179 offset:1024
	ds_read_b64_tr_b16 v[42:43], v179 offset:1536
	s_cmp_lt_i32 s8, s50
	s_waitcnt lgkmcnt(0)
	v_mfma_f32_32x32x16_bf16 v[16:31], v[40:43], v[36:39], v[16:31]
	ds_read_b64_tr_b16 v[40:41], v179 offset:2048
	ds_read_b64_tr_b16 v[42:43], v179 offset:2560
	s_waitcnt lgkmcnt(0)
	v_mfma_f32_32x32x16_bf16 v[0:15], v[40:43], v[32:35], v[0:15]
	ds_read_b64_tr_b16 v[32:33], v179 offset:3072
	ds_read_b64_tr_b16 v[34:35], v179 offset:3584
	s_waitcnt lgkmcnt(0)
	v_mfma_f32_32x32x16_bf16 v[0:15], v[32:35], v[36:39], v[0:15]
	s_cbranch_scc1 .LBB0_1253
	s_waitcnt vmcnt(15)
	v_mfma_f32_32x32x16_bf16 v[32:47], v[76:79], v[48:51], 0
	s_mov_b32 s0, 1
	s_waitcnt lgkmcnt(0)
	s_waitcnt vmcnt(11)
	ds_write_b128 v178, v[96:99]
	s_waitcnt vmcnt(10)
	ds_write_b128 v178, v[100:103] offset:512
	s_waitcnt vmcnt(9)
	ds_write_b128 v178, v[104:107] offset:1024
	s_waitcnt vmcnt(8)
	ds_write_b128 v178, v[108:111] offset:1536
	v_lshl_add_u32 v64, s0, 5, v177
	v_sub_u32_e32 v66, v167, v64
	v_cvt_f32_i32_e32 v211, v66
	v_mfma_f32_32x32x16_bf16 v[32:47], v[80:83], v[52:55], v[32:47]
	v_lshlrev_b32_e32 v68, s30, v64
	v_cmp_gt_u32_e32 vcc, s6, v66
	v_cmp_lt_i32_e64 s[0:1], s3, v68
	v_or_b32_e32 v66, 1, v64
	s_and_b64 vcc, vcc, s[0:1]
	v_mfma_f32_32x32x16_bf16 v[32:47], v[84:87], v[56:59], v[32:47]
	v_mfma_f32_32x32x16_bf16 v[32:47], v[88:91], v[60:63], v[32:47]
	s_nop 11
	v_sub_u32_e32 v170, v167, v64
	v_add_u32_e32 v211, 0xffffffe5, v170
	v_cmp_le_u32_e32 vcc, 0x66, v211
	v_lshlrev_b32_e32 v211, s30, v64
	s_nop 2
	s_cbranch_vccnz .Ldil_slow_3
	v_cmp_ge_i32_e32 vcc, s3, v211
	s_nop 3
	s_cbranch_vccnz .Ldil_slow_3
	v_cvt_f32_i32_e32 v170, v170
	v_mul_f32_e32 v170, v171, v170
	v_fma_f32 v32, v32, v210, -v170
	v_fma_f32 v33, v33, v210, -v170
	v_fmamk_f32 v33, v171, 0x3f800000, v33
	v_fma_f32 v68, v34, v210, -v170
	v_fmamk_f32 v68, v171, 0x40000000, v68
	v_fma_f32 v69, v35, v210, -v170
	v_fmamk_f32 v69, v171, 0x40400000, v69
	v_fma_f32 v70, v36, v210, -v170
	v_fmamk_f32 v70, v171, 0x41000000, v70
	v_fma_f32 v37, v37, v210, -v170
	v_fmamk_f32 v37, v171, 0x41100000, v37
	v_fma_f32 v71, v38, v210, -v170
	v_fmamk_f32 v71, v171, 0x41200000, v71
	v_fma_f32 v39, v39, v210, -v170
	v_fmamk_f32 v39, v171, 0x41300000, v39
	v_fma_f32 v72, v40, v210, -v170
	v_fmamk_f32 v72, v171, 0x41800000, v72
	v_fma_f32 v41, v41, v210, -v170
	v_fmamk_f32 v41, v171, 0x41880000, v41
	v_fma_f32 v73, v42, v210, -v170
	v_fmamk_f32 v73, v171, 0x41900000, v73
	v_fma_f32 v43, v43, v210, -v170
	v_fmamk_f32 v43, v171, 0x41980000, v43
	v_fma_f32 v74, v44, v210, -v170
	v_fmamk_f32 v74, v171, 0x41c00000, v74
	v_fma_f32 v75, v45, v210, -v170
	v_fmamk_f32 v75, v171, 0x41c80000, v75
	v_fma_f32 v76, v46, v210, -v170
	v_fmamk_f32 v76, v171, 0x41d00000, v76
	v_fma_f32 v34, v47, v210, -v170
	v_fmamk_f32 v34, v171, 0x41d80000, v34
	s_branch .Ldil_join_3
.Ldil_slow_3:
	v_sub_u32_e32 v66, v167, v64
	v_cvt_f32_i32_e32 v211, v66
	v_lshlrev_b32_e32 v68, s30, v64
	v_cmp_gt_u32_e32 vcc, s6, v66
	v_cmp_lt_i32_e64 s[0:1], s3, v68
	v_or_b32_e32 v66, 1, v64
	s_and_b64 vcc, vcc, s[0:1]
	v_mov_b32_e32 v170, v32
	v_pk_mul_f32 v[68:69], v[170:171], v[210:211]
	v_mov_b32_e32 v170, v33
	v_sub_f32_e32 v32, v68, v69
	v_sub_u32_e32 v68, v167, v66
	v_cvt_f32_i32_e32 v211, v68
	v_lshlrev_b32_e32 v66, s30, v66
	v_cndmask_b32_e32 v32, v243, v32, vcc
	v_cmp_gt_u32_e32 vcc, s6, v68
	v_cmp_lt_i32_e64 s[0:1], s3, v66
	v_pk_mul_f32 v[68:69], v[170:171], v[210:211]
	v_or_b32_e32 v66, 2, v64
	v_sub_f32_e32 v33, v68, v69
	v_sub_u32_e32 v68, v167, v66
	v_cvt_f32_i32_e32 v211, v68
	s_and_b64 vcc, vcc, s[0:1]
	v_lshlrev_b32_e32 v66, s30, v66
	v_mov_b32_e32 v170, v34
	v_cndmask_b32_e32 v33, v243, v33, vcc
	v_cmp_gt_u32_e32 vcc, s6, v68
	v_cmp_lt_i32_e64 s[0:1], s3, v66
	v_pk_mul_f32 v[68:69], v[170:171], v[210:211]
	s_and_b64 vcc, vcc, s[0:1]
	v_sub_f32_e32 v34, v68, v69
	v_cndmask_b32_e32 v68, v243, v34, vcc
	v_or_b32_e32 v34, 3, v64
	v_sub_u32_e32 v66, v167, v34
	v_cvt_f32_i32_e32 v211, v66
	v_lshlrev_b32_e32 v34, s30, v34
	v_mov_b32_e32 v170, v35
	v_cmp_gt_u32_e32 vcc, s6, v66
	v_cmp_lt_i32_e64 s[0:1], s3, v34
	v_pk_mul_f32 v[34:35], v[170:171], v[210:211]
	s_and_b64 vcc, vcc, s[0:1]
	v_sub_f32_e32 v34, v34, v35
	v_cndmask_b32_e32 v69, v243, v34, vcc
	v_or_b32_e32 v34, 8, v64
	v_sub_u32_e32 v35, v167, v34
	v_cvt_f32_i32_e32 v211, v35
	v_lshlrev_b32_e32 v34, s30, v34
	v_mov_b32_e32 v170, v36
	v_cmp_gt_u32_e32 vcc, s6, v35
	v_cmp_lt_i32_e64 s[0:1], s3, v34
	v_pk_mul_f32 v[34:35], v[170:171], v[210:211]
	s_and_b64 vcc, vcc, s[0:1]
	v_sub_f32_e32 v34, v34, v35
	v_cndmask_b32_e32 v70, v243, v34, vcc
	v_or_b32_e32 v34, 9, v64
	v_sub_u32_e32 v35, v167, v34
	v_cvt_f32_i32_e32 v211, v35
	v_lshlrev_b32_e32 v34, s30, v34
	v_mov_b32_e32 v170, v37
	v_cmp_gt_u32_e32 vcc, s6, v35
	v_cmp_lt_i32_e64 s[0:1], s3, v34
	v_pk_mul_f32 v[34:35], v[170:171], v[210:211]
	s_and_b64 vcc, vcc, s[0:1]
	v_sub_f32_e32 v34, v34, v35
	v_cndmask_b32_e32 v37, v243, v34, vcc
	v_or_b32_e32 v34, 10, v64
	v_sub_u32_e32 v35, v167, v34
	v_cvt_f32_i32_e32 v211, v35
	v_lshlrev_b32_e32 v34, s30, v34
	v_mov_b32_e32 v170, v38
	v_cmp_gt_u32_e32 vcc, s6, v35
	v_cmp_lt_i32_e64 s[0:1], s3, v34
	v_pk_mul_f32 v[34:35], v[170:171], v[210:211]
	s_and_b64 vcc, vcc, s[0:1]
	v_sub_f32_e32 v34, v34, v35
	v_cndmask_b32_e32 v71, v243, v34, vcc
	v_or_b32_e32 v34, 11, v64
	v_sub_u32_e32 v35, v167, v34
	v_cvt_f32_i32_e32 v211, v35
	v_lshlrev_b32_e32 v34, s30, v34
	v_mov_b32_e32 v170, v39
	v_cmp_gt_u32_e32 vcc, s6, v35
	v_cmp_lt_i32_e64 s[0:1], s3, v34
	v_pk_mul_f32 v[34:35], v[170:171], v[210:211]
	s_and_b64 vcc, vcc, s[0:1]
	v_sub_f32_e32 v34, v34, v35
	v_cndmask_b32_e32 v39, v243, v34, vcc
	v_or_b32_e32 v34, 16, v64
	v_sub_u32_e32 v35, v167, v34
	v_cvt_f32_i32_e32 v211, v35
	v_lshlrev_b32_e32 v34, s30, v34
	v_mov_b32_e32 v170, v40
	v_cmp_gt_u32_e32 vcc, s6, v35
	v_cmp_lt_i32_e64 s[0:1], s3, v34
	v_pk_mul_f32 v[34:35], v[170:171], v[210:211]
	s_and_b64 vcc, vcc, s[0:1]
	v_sub_f32_e32 v34, v34, v35
	v_cndmask_b32_e32 v72, v243, v34, vcc
	v_or_b32_e32 v34, 17, v64
	v_sub_u32_e32 v35, v167, v34
	v_cvt_f32_i32_e32 v211, v35
	v_lshlrev_b32_e32 v34, s30, v34
	v_mov_b32_e32 v170, v41
	v_cmp_gt_u32_e32 vcc, s6, v35
	v_cmp_lt_i32_e64 s[0:1], s3, v34
	v_pk_mul_f32 v[34:35], v[170:171], v[210:211]
	s_and_b64 vcc, vcc, s[0:1]
	v_sub_f32_e32 v34, v34, v35
	v_cndmask_b32_e32 v41, v243, v34, vcc
	v_or_b32_e32 v34, 18, v64
	v_sub_u32_e32 v35, v167, v34
	v_cvt_f32_i32_e32 v211, v35
	v_lshlrev_b32_e32 v34, s30, v34
	v_mov_b32_e32 v170, v42
	v_cmp_gt_u32_e32 vcc, s6, v35
	v_cmp_lt_i32_e64 s[0:1], s3, v34
	v_pk_mul_f32 v[34:35], v[170:171], v[210:211]
	s_and_b64 vcc, vcc, s[0:1]
	v_sub_f32_e32 v34, v34, v35
	v_cndmask_b32_e32 v73, v243, v34, vcc
	v_or_b32_e32 v34, 19, v64
	v_sub_u32_e32 v35, v167, v34
	v_cvt_f32_i32_e32 v211, v35
	v_lshlrev_b32_e32 v34, s30, v34
	v_mov_b32_e32 v170, v43
	v_cmp_gt_u32_e32 vcc, s6, v35
	v_cmp_lt_i32_e64 s[0:1], s3, v34
	v_pk_mul_f32 v[34:35], v[170:171], v[210:211]
	s_and_b64 vcc, vcc, s[0:1]
	v_sub_f32_e32 v34, v34, v35
	v_cndmask_b32_e32 v43, v243, v34, vcc
	v_or_b32_e32 v34, 24, v64
	v_sub_u32_e32 v35, v167, v34
	v_cvt_f32_i32_e32 v211, v35
	v_lshlrev_b32_e32 v34, s30, v34
	v_mov_b32_e32 v170, v44
	v_cmp_gt_u32_e32 vcc, s6, v35
	v_cmp_lt_i32_e64 s[0:1], s3, v34
	v_pk_mul_f32 v[34:35], v[170:171], v[210:211]
	s_and_b64 vcc, vcc, s[0:1]
	v_sub_f32_e32 v34, v34, v35
	v_cndmask_b32_e32 v74, v243, v34, vcc
	v_or_b32_e32 v34, 25, v64
	v_sub_u32_e32 v35, v167, v34
	v_cvt_f32_i32_e32 v211, v35
	v_lshlrev_b32_e32 v34, s30, v34
	v_mov_b32_e32 v170, v45
	v_cmp_gt_u32_e32 vcc, s6, v35
	v_cmp_lt_i32_e64 s[0:1], s3, v34
	v_pk_mul_f32 v[34:35], v[170:171], v[210:211]
	s_and_b64 vcc, vcc, s[0:1]
	v_sub_f32_e32 v34, v34, v35
	v_cndmask_b32_e32 v75, v243, v34, vcc
	v_or_b32_e32 v34, 26, v64
	v_sub_u32_e32 v35, v167, v34
	v_cvt_f32_i32_e32 v211, v35
	v_lshlrev_b32_e32 v34, s30, v34
	v_mov_b32_e32 v170, v46
	v_cmp_gt_u32_e32 vcc, s6, v35
	v_cmp_lt_i32_e64 s[0:1], s3, v34
	v_pk_mul_f32 v[34:35], v[170:171], v[210:211]
	s_and_b64 vcc, vcc, s[0:1]
	v_sub_f32_e32 v34, v34, v35
	v_cndmask_b32_e32 v76, v243, v34, vcc
	v_or_b32_e32 v34, 27, v64
	v_sub_u32_e32 v35, v167, v34
	v_cvt_f32_i32_e32 v211, v35
	v_lshlrev_b32_e32 v34, s30, v34
	v_mov_b32_e32 v170, v47
	v_cmp_gt_u32_e32 vcc, s6, v35
	v_cmp_lt_i32_e64 s[0:1], s3, v34
	v_pk_mul_f32 v[34:35], v[170:171], v[210:211]
	s_and_b64 vcc, vcc, s[0:1]
	v_sub_f32_e32 v34, v34, v35
	v_cndmask_b32_e32 v34, v243, v34, vcc
; __device__ __forceinline__ void dil_unit(const bf16_t* QKV, float* scr, bf16_t* O, int b, int h, int blk, char* shm) {
;     ...
;                         if (DIL_LIVE(0)) DIL_TILE(0, kfB, vrB);
.Ldil_join_3:
	v_max_f32_e32 v42, v76, v34
	v_max_f32_e32 v35, v68, v69
	v_max_f32_e32 v36, v71, v39
	v_max_f32_e32 v38, v72, v41
	v_max_f32_e32 v40, v73, v43
	v_max3_f32 v42, v74, v75, v42
	v_max3_f32 v35, v32, v33, v35
	v_max3_f32 v36, v70, v37, v36
	v_max3_f32 v38, v38, v40, v42
	v_max3_f32 v35, v35, v36, v38
	v_mov_b32_e32 v36, v35
	s_nop 1
	v_permlane32_swap_b32_e32 v35, v36
	v_max3_f32 v66, v67, v35, v36
	v_sub_f32_e32 v32, v32, v66
	v_exp_f32_e32 v36, v32
	v_sub_f32_e32 v32, v33, v66
	v_exp_f32_e32 v38, v32
	v_sub_f32_e32 v32, v68, v66
	v_exp_f32_e32 v40, v32
	v_sub_f32_e32 v32, v69, v66
	v_exp_f32_e32 v42, v32
	v_sub_f32_e32 v32, v70, v66
	v_exp_f32_e32 v44, v32
	v_sub_f32_e32 v32, v37, v66
	v_exp_f32_e32 v46, v32
	v_sub_f32_e32 v32, v71, v66
	v_exp_f32_e32 v68, v32
	v_sub_f32_e32 v32, v39, v66
	v_exp_f32_e32 v70, v32
	v_sub_f32_e32 v32, v72, v66
	v_exp_f32_e32 v37, v32
	v_sub_f32_e32 v32, v41, v66
	v_exp_f32_e32 v39, v32
	v_sub_f32_e32 v32, v73, v66
	v_exp_f32_e32 v41, v32
	v_sub_f32_e32 v32, v43, v66
	v_exp_f32_e32 v43, v32
	v_sub_f32_e32 v32, v74, v66
	v_exp_f32_e32 v45, v32
	v_sub_f32_e32 v32, v75, v66
	v_exp_f32_e32 v47, v32
	v_sub_f32_e32 v32, v76, v66
	v_exp_f32_e32 v69, v32
	v_sub_f32_e32 v32, v34, v66
	v_exp_f32_e32 v71, v32
	v_sub_f32_e32 v35, v67, v66
	v_exp_f32_e32 v32, v35
	v_pk_add_f32 v[34:35], v[36:37], v[38:39]
	v_pk_add_f32 v[72:73], v[40:41], v[42:43]
	v_pk_add_f32 v[74:75], v[68:69], v[70:71]
	v_pk_add_f32 v[34:35], v[34:35], v[72:73]
	v_pk_add_f32 v[72:73], v[44:45], v[46:47]
	v_pk_mul_f32 v[30:31], v[30:31], v[32:33] op_sel_hi:[1,0]
	v_pk_add_f32 v[72:73], v[72:73], v[74:75]
	v_pk_mul_f32 v[28:29], v[28:29], v[32:33] op_sel_hi:[1,0]
	v_pk_add_f32 v[34:35], v[34:35], v[72:73]
	v_pk_mul_f32 v[26:27], v[26:27], v[32:33] op_sel_hi:[1,0]
	v_add_f32_e32 v64, v34, v35
	v_pk_mul_f32 v[24:25], v[24:25], v[32:33] op_sel_hi:[1,0]
	v_pk_mul_f32 v[22:23], v[22:23], v[32:33] op_sel_hi:[1,0]
	v_pk_mul_f32 v[20:21], v[20:21], v[32:33] op_sel_hi:[1,0]
	v_pk_mul_f32 v[18:19], v[18:19], v[32:33] op_sel_hi:[1,0]
	v_pk_mul_f32 v[16:17], v[16:17], v[32:33] op_sel_hi:[1,0]
	v_pk_mul_f32 v[14:15], v[14:15], v[32:33] op_sel_hi:[1,0]
	v_pk_mul_f32 v[12:13], v[12:13], v[32:33] op_sel_hi:[1,0]
	v_pk_mul_f32 v[10:11], v[10:11], v[32:33] op_sel_hi:[1,0]
	v_pk_mul_f32 v[8:9], v[8:9], v[32:33] op_sel_hi:[1,0]
	v_pk_mul_f32 v[6:7], v[6:7], v[32:33] op_sel_hi:[1,0]
	v_pk_mul_f32 v[4:5], v[4:5], v[32:33] op_sel_hi:[1,0]
	v_pk_mul_f32 v[2:3], v[2:3], v[32:33] op_sel_hi:[1,0]
	v_pk_mul_f32 v[0:1], v[0:1], v[32:33] op_sel_hi:[1,0]
	v_fmac_f32_e32 v64, v65, v32
	v_cvt_pk_bf16_f32 v32, v36, v38
	v_cvt_pk_bf16_f32 v33, v40, v42
	v_cvt_pk_bf16_f32 v34, v44, v46
	v_cvt_pk_bf16_f32 v35, v68, v70
	v_cvt_pk_bf16_f32 v36, v37, v39
	v_cvt_pk_bf16_f32 v37, v41, v43
	v_cvt_pk_bf16_f32 v38, v45, v47
	v_cvt_pk_bf16_f32 v39, v69, v71
	s_waitcnt lgkmcnt(0)
	ds_read_b64_tr_b16 v[40:41], v179
	ds_read_b64_tr_b16 v[42:43], v179 offset:512
	s_waitcnt lgkmcnt(0)
	v_mfma_f32_32x32x16_bf16 v[16:31], v[40:43], v[32:35], v[16:31]
	ds_read_b64_tr_b16 v[40:41], v179 offset:1024
	ds_read_b64_tr_b16 v[42:43], v179 offset:1536
	s_cmp_lt_i32 s8, s51
	s_waitcnt lgkmcnt(0)
	v_mfma_f32_32x32x16_bf16 v[16:31], v[40:43], v[36:39], v[16:31]
	ds_read_b64_tr_b16 v[40:41], v179 offset:2048
	ds_read_b64_tr_b16 v[42:43], v179 offset:2560
	s_waitcnt lgkmcnt(0)
	v_mfma_f32_32x32x16_bf16 v[0:15], v[40:43], v[32:35], v[0:15]
	ds_read_b64_tr_b16 v[32:33], v179 offset:3072
	ds_read_b64_tr_b16 v[34:35], v179 offset:3584
	s_waitcnt lgkmcnt(0)
	v_mfma_f32_32x32x16_bf16 v[0:15], v[32:35], v[36:39], v[0:15]
	s_cbranch_scc1 .LBB0_1252
	s_waitcnt vmcnt(7)
	v_mfma_f32_32x32x16_bf16 v[32:47], v[124:127], v[48:51], 0
	s_mov_b32 s0, s19
	s_waitcnt lgkmcnt(0)
	s_waitcnt vmcnt(3)
	ds_write_b128 v178, v[144:147]
	s_waitcnt vmcnt(2)
	ds_write_b128 v178, v[148:151] offset:512
	s_waitcnt vmcnt(1)
	ds_write_b128 v178, v[152:155] offset:1024
	s_waitcnt vmcnt(0)
	ds_write_b128 v178, v[156:159] offset:1536
	v_lshl_add_u32 v48, s0, 5, v177
	v_sub_u32_e32 v49, v167, v48
	v_cvt_f32_i32_e32 v211, v49
	v_mfma_f32_32x32x16_bf16 v[32:47], v[128:131], v[52:55], v[32:47]
	v_lshlrev_b32_e32 v50, s30, v48
	v_cmp_gt_u32_e32 vcc, s6, v49
	v_cmp_lt_i32_e64 s[0:1], s3, v50
	v_or_b32_e32 v49, 1, v48
	s_and_b64 vcc, vcc, s[0:1]
	v_mfma_f32_32x32x16_bf16 v[32:47], v[132:135], v[56:59], v[32:47]
	v_mfma_f32_32x32x16_bf16 v[32:47], v[136:139], v[60:63], v[32:47]
	s_nop 11
	v_mov_b32_e32 v170, v32
	v_pk_mul_f32 v[50:51], v[170:171], v[210:211]
	v_mov_b32_e32 v170, v33
	v_sub_f32_e32 v32, v50, v51
	v_sub_u32_e32 v50, v167, v49
	v_cvt_f32_i32_e32 v211, v50
	v_lshlrev_b32_e32 v49, s30, v49
	v_cndmask_b32_e32 v32, v243, v32, vcc
	v_cmp_gt_u32_e32 vcc, s6, v50
	v_cmp_lt_i32_e64 s[0:1], s3, v49
	v_pk_mul_f32 v[50:51], v[170:171], v[210:211]
	v_or_b32_e32 v49, 2, v48
	v_sub_f32_e32 v33, v50, v51
	v_sub_u32_e32 v50, v167, v49
	v_cvt_f32_i32_e32 v211, v50
	s_and_b64 vcc, vcc, s[0:1]
	v_lshlrev_b32_e32 v49, s30, v49
	v_mov_b32_e32 v170, v34
	v_cndmask_b32_e32 v33, v243, v33, vcc
	v_cmp_gt_u32_e32 vcc, s6, v50
	v_cmp_lt_i32_e64 s[0:1], s3, v49
	v_pk_mul_f32 v[50:51], v[170:171], v[210:211]
	s_and_b64 vcc, vcc, s[0:1]
	v_sub_f32_e32 v34, v50, v51
	v_cndmask_b32_e32 v49, v243, v34, vcc
	v_or_b32_e32 v34, 3, v48
	v_sub_u32_e32 v50, v167, v34
	v_cvt_f32_i32_e32 v211, v50
	v_lshlrev_b32_e32 v34, s30, v34
	v_mov_b32_e32 v170, v35
	v_cmp_gt_u32_e32 vcc, s6, v50
	v_cmp_lt_i32_e64 s[0:1], s3, v34
	v_pk_mul_f32 v[34:35], v[170:171], v[210:211]
	s_and_b64 vcc, vcc, s[0:1]
	v_sub_f32_e32 v34, v34, v35
	v_cndmask_b32_e32 v50, v243, v34, vcc
	v_or_b32_e32 v34, 8, v48
	v_sub_u32_e32 v35, v167, v34
	v_cvt_f32_i32_e32 v211, v35
	v_lshlrev_b32_e32 v34, s30, v34
	v_mov_b32_e32 v170, v36
	v_cmp_gt_u32_e32 vcc, s6, v35
	v_cmp_lt_i32_e64 s[0:1], s3, v34
	v_pk_mul_f32 v[34:35], v[170:171], v[210:211]
	s_and_b64 vcc, vcc, s[0:1]
	v_sub_f32_e32 v34, v34, v35
	v_cndmask_b32_e32 v51, v243, v34, vcc
	v_or_b32_e32 v34, 9, v48
	v_sub_u32_e32 v35, v167, v34
	v_cvt_f32_i32_e32 v211, v35
	v_lshlrev_b32_e32 v34, s30, v34
	v_mov_b32_e32 v170, v37
	v_cmp_gt_u32_e32 vcc, s6, v35
	v_cmp_lt_i32_e64 s[0:1], s3, v34
	v_pk_mul_f32 v[34:35], v[170:171], v[210:211]
	s_and_b64 vcc, vcc, s[0:1]
	v_sub_f32_e32 v34, v34, v35
	v_cndmask_b32_e32 v37, v243, v34, vcc
	v_or_b32_e32 v34, 10, v48
	v_sub_u32_e32 v35, v167, v34
	v_cvt_f32_i32_e32 v211, v35
	v_lshlrev_b32_e32 v34, s30, v34
	v_mov_b32_e32 v170, v38
	v_cmp_gt_u32_e32 vcc, s6, v35
	v_cmp_lt_i32_e64 s[0:1], s3, v34
	v_pk_mul_f32 v[34:35], v[170:171], v[210:211]
	s_and_b64 vcc, vcc, s[0:1]
	v_sub_f32_e32 v34, v34, v35
	v_cndmask_b32_e32 v52, v243, v34, vcc
	v_or_b32_e32 v34, 11, v48
	v_sub_u32_e32 v35, v167, v34
	v_cvt_f32_i32_e32 v211, v35
	v_lshlrev_b32_e32 v34, s30, v34
	v_mov_b32_e32 v170, v39
	v_cmp_gt_u32_e32 vcc, s6, v35
	v_cmp_lt_i32_e64 s[0:1], s3, v34
	v_pk_mul_f32 v[34:35], v[170:171], v[210:211]
	s_and_b64 vcc, vcc, s[0:1]
	v_sub_f32_e32 v34, v34, v35
	v_cndmask_b32_e32 v39, v243, v34, vcc
	v_or_b32_e32 v34, 16, v48
	v_sub_u32_e32 v35, v167, v34
	v_cvt_f32_i32_e32 v211, v35
	v_lshlrev_b32_e32 v34, s30, v34
	v_mov_b32_e32 v170, v40
	v_cmp_gt_u32_e32 vcc, s6, v35
	v_cmp_lt_i32_e64 s[0:1], s3, v34
	v_pk_mul_f32 v[34:35], v[170:171], v[210:211]
	s_and_b64 vcc, vcc, s[0:1]
	v_sub_f32_e32 v34, v34, v35
	v_cndmask_b32_e32 v53, v243, v34, vcc
	v_or_b32_e32 v34, 17, v48
	v_sub_u32_e32 v35, v167, v34
	v_cvt_f32_i32_e32 v211, v35
	v_lshlrev_b32_e32 v34, s30, v34
	v_mov_b32_e32 v170, v41
	v_cmp_gt_u32_e32 vcc, s6, v35
	v_cmp_lt_i32_e64 s[0:1], s3, v34
	v_pk_mul_f32 v[34:35], v[170:171], v[210:211]
	s_and_b64 vcc, vcc, s[0:1]
	v_sub_f32_e32 v34, v34, v35
	v_cndmask_b32_e32 v41, v243, v34, vcc
	v_or_b32_e32 v34, 18, v48
	v_sub_u32_e32 v35, v167, v34
	v_cvt_f32_i32_e32 v211, v35
	v_lshlrev_b32_e32 v34, s30, v34
	v_mov_b32_e32 v170, v42
	v_cmp_gt_u32_e32 vcc, s6, v35
	v_cmp_lt_i32_e64 s[0:1], s3, v34
	v_pk_mul_f32 v[34:35], v[170:171], v[210:211]
	s_and_b64 vcc, vcc, s[0:1]
	v_sub_f32_e32 v34, v34, v35
	v_cndmask_b32_e32 v42, v243, v34, vcc
	v_or_b32_e32 v34, 19, v48
	v_sub_u32_e32 v35, v167, v34
	v_cvt_f32_i32_e32 v211, v35
	v_lshlrev_b32_e32 v34, s30, v34
	v_mov_b32_e32 v170, v43
	v_cmp_gt_u32_e32 vcc, s6, v35
	v_cmp_lt_i32_e64 s[0:1], s3, v34
	v_pk_mul_f32 v[34:35], v[170:171], v[210:211]
	s_and_b64 vcc, vcc, s[0:1]
	v_sub_f32_e32 v34, v34, v35
	v_cndmask_b32_e32 v43, v243, v34, vcc
	v_or_b32_e32 v34, 24, v48
	v_sub_u32_e32 v35, v167, v34
	v_cvt_f32_i32_e32 v211, v35
	v_lshlrev_b32_e32 v34, s30, v34
	v_mov_b32_e32 v170, v44
	v_cmp_gt_u32_e32 vcc, s6, v35
	v_cmp_lt_i32_e64 s[0:1], s3, v34
	v_pk_mul_f32 v[34:35], v[170:171], v[210:211]
	s_and_b64 vcc, vcc, s[0:1]
	v_sub_f32_e32 v34, v34, v35
	v_cndmask_b32_e32 v44, v243, v34, vcc
	v_or_b32_e32 v34, 25, v48
	v_sub_u32_e32 v35, v167, v34
	v_cvt_f32_i32_e32 v211, v35
	v_lshlrev_b32_e32 v34, s30, v34
	v_mov_b32_e32 v170, v45
	v_cmp_gt_u32_e32 vcc, s6, v35
	v_cmp_lt_i32_e64 s[0:1], s3, v34
	v_pk_mul_f32 v[34:35], v[170:171], v[210:211]
	s_and_b64 vcc, vcc, s[0:1]
	v_sub_f32_e32 v34, v34, v35
	v_cndmask_b32_e32 v45, v243, v34, vcc
	v_or_b32_e32 v34, 26, v48
	v_sub_u32_e32 v35, v167, v34
	v_cvt_f32_i32_e32 v211, v35
	v_lshlrev_b32_e32 v34, s30, v34
	v_mov_b32_e32 v170, v46
	v_cmp_gt_u32_e32 vcc, s6, v35
	v_cmp_lt_i32_e64 s[0:1], s3, v34
	v_pk_mul_f32 v[34:35], v[170:171], v[210:211]
	s_and_b64 vcc, vcc, s[0:1]
	v_sub_f32_e32 v34, v34, v35
	v_cndmask_b32_e32 v54, v243, v34, vcc
	v_or_b32_e32 v34, 27, v48
	v_sub_u32_e32 v35, v167, v34
	v_cvt_f32_i32_e32 v211, v35
	v_lshlrev_b32_e32 v34, s30, v34
	v_mov_b32_e32 v170, v47
	v_cmp_gt_u32_e32 vcc, s6, v35
	v_cmp_lt_i32_e64 s[0:1], s3, v34
	v_pk_mul_f32 v[34:35], v[170:171], v[210:211]
	s_and_b64 vcc, vcc, s[0:1]
	v_sub_f32_e32 v34, v34, v35
	v_cndmask_b32_e32 v55, v243, v34, vcc
	v_max_f32_e32 v40, v54, v55
	v_max_f32_e32 v34, v49, v50
	v_max_f32_e32 v35, v52, v39
	v_max_f32_e32 v36, v53, v41
	v_max_f32_e32 v38, v42, v43
	v_max3_f32 v40, v44, v45, v40
	v_max3_f32 v34, v32, v33, v34
	v_max3_f32 v35, v51, v37, v35
	v_max3_f32 v36, v36, v38, v40
	v_max3_f32 v34, v34, v35, v36
	v_mov_b32_e32 v35, v34
	s_nop 1
	v_permlane32_swap_b32_e32 v34, v35
	v_max3_f32 v56, v66, v34, v35
	v_sub_f32_e32 v33, v33, v56
	v_exp_f32_e32 v34, v33
	v_sub_f32_e32 v33, v49, v56
	v_exp_f32_e32 v36, v33
	v_sub_f32_e32 v33, v50, v56
	v_exp_f32_e32 v38, v33
	v_sub_f32_e32 v33, v51, v56
	v_exp_f32_e32 v40, v33
	v_sub_f32_e32 v33, v37, v56
	v_exp_f32_e32 v46, v33
	v_sub_f32_e32 v33, v52, v56
	v_exp_f32_e32 v48, v33
	v_sub_f32_e32 v33, v39, v56
	v_sub_f32_e32 v37, v42, v56
	v_sub_f32_e32 v42, v45, v56
	v_sub_f32_e32 v32, v32, v56
	v_exp_f32_e32 v50, v33
	v_sub_f32_e32 v33, v53, v56
	v_sub_f32_e32 v35, v41, v56
	v_sub_f32_e32 v39, v43, v56
	v_exp_f32_e32 v47, v42
	v_sub_f32_e32 v42, v54, v56
	v_exp_f32_e32 v32, v32
	v_exp_f32_e32 v33, v33
	v_exp_f32_e32 v35, v35
	v_exp_f32_e32 v37, v37
	v_exp_f32_e32 v39, v39
	v_sub_f32_e32 v41, v44, v56
	v_exp_f32_e32 v49, v42
	v_sub_f32_e32 v42, v55, v56
	v_exp_f32_e32 v41, v41
	v_exp_f32_e32 v51, v42
	v_sub_f32_e32 v57, v66, v56
	v_pk_add_f32 v[44:45], v[32:33], v[34:35]
	v_pk_add_f32 v[52:53], v[36:37], v[38:39]
	v_exp_f32_e32 v42, v57
	v_pk_add_f32 v[44:45], v[44:45], v[52:53]
	v_pk_add_f32 v[52:53], v[40:41], v[46:47]
	v_pk_add_f32 v[54:55], v[48:49], v[50:51]
	v_pk_mul_f32 v[30:31], v[30:31], v[42:43] op_sel_hi:[1,0]
	v_pk_add_f32 v[52:53], v[52:53], v[54:55]
	v_pk_mul_f32 v[28:29], v[28:29], v[42:43] op_sel_hi:[1,0]
	v_pk_add_f32 v[44:45], v[44:45], v[52:53]
	v_pk_mul_f32 v[26:27], v[26:27], v[42:43] op_sel_hi:[1,0]
	v_add_f32_e32 v52, v44, v45
	v_pk_mul_f32 v[24:25], v[24:25], v[42:43] op_sel_hi:[1,0]
	v_pk_mul_f32 v[22:23], v[22:23], v[42:43] op_sel_hi:[1,0]
	v_pk_mul_f32 v[20:21], v[20:21], v[42:43] op_sel_hi:[1,0]
	v_pk_mul_f32 v[18:19], v[18:19], v[42:43] op_sel_hi:[1,0]
	v_pk_mul_f32 v[16:17], v[16:17], v[42:43] op_sel_hi:[1,0]
	v_pk_mul_f32 v[14:15], v[14:15], v[42:43] op_sel_hi:[1,0]
	v_pk_mul_f32 v[12:13], v[12:13], v[42:43] op_sel_hi:[1,0]
	v_pk_mul_f32 v[10:11], v[10:11], v[42:43] op_sel_hi:[1,0]
	v_pk_mul_f32 v[8:9], v[8:9], v[42:43] op_sel_hi:[1,0]
	v_pk_mul_f32 v[6:7], v[6:7], v[42:43] op_sel_hi:[1,0]
	v_pk_mul_f32 v[4:5], v[4:5], v[42:43] op_sel_hi:[1,0]
	v_pk_mul_f32 v[2:3], v[2:3], v[42:43] op_sel_hi:[1,0]
	v_pk_mul_f32 v[0:1], v[0:1], v[42:43] op_sel_hi:[1,0]
	v_fmac_f32_e32 v52, v64, v42
	v_cvt_pk_bf16_f32 v42, v32, v34
	v_cvt_pk_bf16_f32 v43, v36, v38
	v_cvt_pk_bf16_f32 v44, v40, v46
	v_cvt_pk_bf16_f32 v45, v48, v50
	v_cvt_pk_bf16_f32 v32, v33, v35
	v_cvt_pk_bf16_f32 v33, v37, v39
	v_cvt_pk_bf16_f32 v34, v41, v47
	v_cvt_pk_bf16_f32 v35, v49, v51
	s_waitcnt lgkmcnt(0)
	ds_read_b64_tr_b16 v[36:37], v179
	ds_read_b64_tr_b16 v[38:39], v179 offset:512
	s_waitcnt lgkmcnt(0)
	v_mfma_f32_32x32x16_bf16 v[16:31], v[36:39], v[42:45], v[16:31]
	ds_read_b64_tr_b16 v[36:37], v179 offset:1024
	ds_read_b64_tr_b16 v[38:39], v179 offset:1536
	v_mov_b32_e32 v66, v56
	v_mov_b32_e32 v64, v52
	s_waitcnt lgkmcnt(0)
	v_mfma_f32_32x32x16_bf16 v[16:31], v[36:39], v[32:35], v[16:31]
	ds_read_b64_tr_b16 v[36:37], v179 offset:2048
	ds_read_b64_tr_b16 v[38:39], v179 offset:2560
	s_waitcnt lgkmcnt(0)
	v_mfma_f32_32x32x16_bf16 v[0:15], v[36:39], v[42:45], v[0:15]
	ds_read_b64_tr_b16 v[36:37], v179 offset:3072
	ds_read_b64_tr_b16 v[38:39], v179 offset:3584
	s_waitcnt lgkmcnt(0)
	v_mfma_f32_32x32x16_bf16 v[0:15], v[36:39], v[32:35], v[0:15]
